# scan step: pair sums via one packed add + one add (was three adds), y writes of non-owner lanes go to a scratch LDS slot instead of exec narrowing: 52 -> 48 instructions per step
# speedup vs baseline: 1.0121x; 1.0121x over previous
; DI float oct_sum(float v) { v += dpp_f<0xB1>(v); v += dpp_f<0x4E>(v); v += dpp_f<0x141>(v); return v; }
; DI void scan_item(const Params& p, int b, int h, int half, char* smem, unsigned* pgen, unsigned kp) {
;     ...
;       for (int s4 = 0; s4 < 4; ++s4) {
;         const int s = sg + s4;
;         const f32x2* a2 = (const f32x2*)(Al + s * 64 + cg * 8);
;         const f32x2* w2 = (const f32x2*)(Wl + s * 64 + cg * 8);
;         const f32x2* b2 = (const f32x2*)(Bl + s * 64 + cg * 8);
;         const f32x2* k2 = (const f32x2*)(Kl + s * 64 + cg * 8);
;         const f32x2* r2 = (const f32x2*)(Rl + s * 64 + cg * 8);
;         f32x2 o[20];
; #pragma unroll
;         for (int i = 0; i < 4; ++i) { o[i] = a2[i]; o[4 + i] = w2[i]; o[8 + i] = b2[i]; o[12 + i] = k2[i]; o[16 + i] = r2[i]; }
;         const float vr = Vl[s * 64 + 32 * half + rp];
;         f32x2 p0 = St[0] * o[0], p1 = St[1] * o[1];
;         p0 = __builtin_elementwise_fma(St[2], o[2], p0); p1 = __builtin_elementwise_fma(St[3], o[3], p1);
;         const float sa = oct_sum((p0.x + p0.y) + (p1.x + p1.y));
;         const f32x2 sv = {sa, sa}, vv = {vr, vr};
;         f32x2 y0 = {0.f, 0.f}, y1 = {0.f, 0.f};
; #pragma unroll
;         for (int i = 0; i < 4; i += 2) {
;           St[i] = __builtin_elementwise_fma(St[i], o[4 + i], __builtin_elementwise_fma(sv, o[8 + i], vv * o[12 + i]));
;           St[i + 1] = __builtin_elementwise_fma(St[i + 1], o[5 + i], __builtin_elementwise_fma(sv, o[9 + i], vv * o[13 + i]));
;           y0 = __builtin_elementwise_fma(St[i], o[16 + i], y0);
;           y1 = __builtin_elementwise_fma(St[i + 1], o[17 + i], y1);
;         }
;         yy[s4] = oct_sum((y0.x + y0.y) + (y1.x + y1.y));
;       }
;       if (cg == 0) {
; #pragma unroll
;         for (int s4 = 0; s4 < 4; ++s4) Yl[(sg + s4) * 32 + rp] = yy[s4];
.LBB0_701:
	s_mov_b32 s26, -4
	v_mov_b32_e32 v0, v214
	v_mov_b32_e32 v161, v160
	v_lshlrev_b32_e32 v162, 2, v173
	v_add_u32_e32 v162, 0xb000, v162
	v_cndmask_b32_e64 v162, v162, v225, s[12:13]
	ds_read_b128 v[34:37], v0 offset:16384
	ds_read_b128 v[38:41], v0 offset:16400
	ds_read_b128 v[68:71], v0 offset:8192
	ds_read_b128 v[150:153], v0 offset:8208
	ds_read2st64_b32 v[158:159], v161 offset0:0 offset1:1
	ds_read_b128 v[50:53], v0 offset:20480
	ds_read_b128 v[54:57], v0 offset:20496
	ds_read_b128 v[42:45], v0 offset:4096
	ds_read_b128 v[46:49], v0 offset:4112
	ds_read_b128 v[154:157], v0 offset:0
	ds_read_b128 v[246:249], v0 offset:16
	ds_read_b128 v[200:203], v0 offset:16640
	ds_read_b128 v[230:233], v0 offset:16656
	s_waitcnt lgkmcnt(11)
	v_pk_mul_f32 v[34:35], v[66:67], v[34:35]
	v_pk_mul_f32 v[36:37], v[64:65], v[36:37]
	v_pk_fma_f32 v[34:35], v[62:63], v[38:39], v[34:35]
	v_pk_fma_f32 v[36:37], v[60:61], v[40:41], v[36:37]
	v_pk_add_f32 v[34:35], v[34:35], v[36:37]
	v_add_f32_e32 v198, v34, v35
	s_waitcnt lgkmcnt(8)
	v_pk_mul_f32 v[58:59], v[68:69], v[158:159] op_sel_hi:[1,0]
	v_pk_mul_f32 v[72:73], v[70:71], v[158:159] op_sel_hi:[1,0]
	ds_read_b128 v[68:71], v0 offset:8448
	v_add_f32_dpp v198, v198, v198 quad_perm:[1,0,3,2] row_mask:0xf bank_mask:0xf bound_ctrl:1
	s_nop 0
	v_pk_mul_f32 v[212:213], v[150:151], v[158:159] op_sel_hi:[1,0]
	v_add_f32_dpp v198, v198, v198 quad_perm:[2,3,0,1] row_mask:0xf bank_mask:0xf bound_ctrl:1
	s_nop 0
	v_pk_mul_f32 v[250:251], v[152:153], v[158:159] op_sel_hi:[1,0]
	ds_read_b128 v[150:153], v0 offset:8464
	v_add_f32_dpp v198, v198, v198 row_half_mirror row_mask:0xf bank_mask:0xf bound_ctrl:1
	s_waitcnt lgkmcnt(8)
	v_pk_fma_f32 v[58:59], v[198:199], v[50:51], v[58:59] op_sel_hi:[0,1,1]
	v_pk_fma_f32 v[72:73], v[198:199], v[52:53], v[72:73] op_sel_hi:[0,1,1]
	s_waitcnt lgkmcnt(6)
	v_pk_fma_f32 v[66:67], v[66:67], v[42:43], v[58:59]
	v_pk_fma_f32 v[64:65], v[64:65], v[44:45], v[72:73]
	v_pk_fma_f32 v[212:213], v[198:199], v[54:55], v[212:213] op_sel_hi:[0,1,1]
	v_pk_fma_f32 v[250:251], v[198:199], v[56:57], v[250:251] op_sel_hi:[0,1,1]
	v_pk_fma_f32 v[62:63], v[62:63], v[46:47], v[212:213]
	v_pk_fma_f32 v[60:61], v[60:61], v[48:49], v[250:251]
	ds_read_b128 v[50:53], v0 offset:20736
	ds_read_b128 v[54:57], v0 offset:20752
	ds_read_b128 v[42:45], v0 offset:4352
	ds_read_b128 v[46:49], v0 offset:4368
	s_waitcnt lgkmcnt(8)
	v_pk_fma_f32 v[58:59], v[66:67], v[154:155], 0 op_sel_hi:[1,1,0]
	v_pk_fma_f32 v[72:73], v[64:65], v[156:157], 0 op_sel_hi:[1,1,0]
	v_pk_fma_f32 v[58:59], v[62:63], v[246:247], v[58:59]
	v_pk_fma_f32 v[72:73], v[60:61], v[248:249], v[72:73]
	ds_read_b128 v[154:157], v0 offset:256
	ds_read_b128 v[246:249], v0 offset:272
	v_pk_add_f32 v[58:59], v[58:59], v[72:73]
	ds_read_b128 v[34:37], v0 offset:16896
	ds_read_b128 v[38:41], v0 offset:16912
	s_waitcnt lgkmcnt(10)
	v_pk_mul_f32 v[200:201], v[66:67], v[200:201]
	v_pk_mul_f32 v[202:203], v[64:65], v[202:203]
	v_pk_fma_f32 v[200:201], v[62:63], v[230:231], v[200:201]
	v_pk_fma_f32 v[202:203], v[60:61], v[232:233], v[202:203]
	v_pk_add_f32 v[200:201], v[200:201], v[202:203]
	v_add_f32_e32 v207, v58, v59
	v_add_f32_e32 v198, v200, v201
	s_waitcnt lgkmcnt(8)
	v_mov_b32_e32 v232, v159
	v_pk_mul_f32 v[58:59], v[68:69], v[232:233] op_sel_hi:[1,0]
	v_pk_mul_f32 v[72:73], v[70:71], v[232:233] op_sel_hi:[1,0]
	ds_read_b128 v[68:71], v0 offset:8704
	v_add_f32_dpp v198, v198, v198 quad_perm:[1,0,3,2] row_mask:0xf bank_mask:0xf bound_ctrl:1
	v_add_f32_dpp v207, v207, v207 quad_perm:[1,0,3,2] row_mask:0xf bank_mask:0xf bound_ctrl:1
	v_pk_mul_f32 v[212:213], v[150:151], v[232:233] op_sel_hi:[1,0]
	v_add_f32_dpp v198, v198, v198 quad_perm:[2,3,0,1] row_mask:0xf bank_mask:0xf bound_ctrl:1
	v_add_f32_dpp v207, v207, v207 quad_perm:[2,3,0,1] row_mask:0xf bank_mask:0xf bound_ctrl:1
	v_pk_mul_f32 v[250:251], v[152:153], v[232:233] op_sel_hi:[1,0]
	ds_read_b128 v[150:153], v0 offset:8720
	v_add_f32_dpp v198, v198, v198 row_half_mirror row_mask:0xf bank_mask:0xf bound_ctrl:1
	v_add_f32_dpp v163, v207, v207 row_half_mirror row_mask:0xf bank_mask:0xf bound_ctrl:1
	ds_read2st64_b32 v[158:159], v161 offset0:2 offset1:3
	ds_write_b32 v162, v163 offset:0
	s_waitcnt lgkmcnt(9)
	v_pk_fma_f32 v[58:59], v[198:199], v[50:51], v[58:59] op_sel_hi:[0,1,1]
	v_pk_fma_f32 v[72:73], v[198:199], v[52:53], v[72:73] op_sel_hi:[0,1,1]
	s_waitcnt lgkmcnt(7)
	v_pk_fma_f32 v[66:67], v[66:67], v[42:43], v[58:59]
	v_pk_fma_f32 v[64:65], v[64:65], v[44:45], v[72:73]
	v_pk_fma_f32 v[212:213], v[198:199], v[54:55], v[212:213] op_sel_hi:[0,1,1]
	v_pk_fma_f32 v[250:251], v[198:199], v[56:57], v[250:251] op_sel_hi:[0,1,1]
	v_pk_fma_f32 v[62:63], v[62:63], v[46:47], v[212:213]
	v_pk_fma_f32 v[60:61], v[60:61], v[48:49], v[250:251]
	ds_read_b128 v[50:53], v0 offset:20992
	ds_read_b128 v[54:57], v0 offset:21008
	ds_read_b128 v[42:45], v0 offset:4608
	ds_read_b128 v[46:49], v0 offset:4624
	s_waitcnt lgkmcnt(9)
	v_pk_fma_f32 v[58:59], v[66:67], v[154:155], 0 op_sel_hi:[1,1,0]
	v_pk_fma_f32 v[72:73], v[64:65], v[156:157], 0 op_sel_hi:[1,1,0]
	v_pk_fma_f32 v[58:59], v[62:63], v[246:247], v[58:59]
	v_pk_fma_f32 v[72:73], v[60:61], v[248:249], v[72:73]
	ds_read_b128 v[154:157], v0 offset:512
	ds_read_b128 v[246:249], v0 offset:528
	v_pk_add_f32 v[58:59], v[58:59], v[72:73]
	ds_read_b128 v[200:203], v0 offset:17152
	ds_read_b128 v[230:233], v0 offset:17168
	s_waitcnt lgkmcnt(11)
	v_pk_mul_f32 v[34:35], v[66:67], v[34:35]
	v_pk_mul_f32 v[36:37], v[64:65], v[36:37]
	v_pk_fma_f32 v[34:35], v[62:63], v[38:39], v[34:35]
	v_pk_fma_f32 v[36:37], v[60:61], v[40:41], v[36:37]
	v_pk_add_f32 v[34:35], v[34:35], v[36:37]
	v_add_f32_e32 v207, v58, v59
	v_add_f32_e32 v198, v34, v35
	s_waitcnt lgkmcnt(8)
; DI float oct_sum(float v) { v += dpp_f<0xB1>(v); v += dpp_f<0x4E>(v); v += dpp_f<0x141>(v); return v; }
; DI void scan_item(const Params& p, int b, int h, int half, char* smem, unsigned* pgen, unsigned kp) {
;     ...
;       for (int s4 = 0; s4 < 4; ++s4) {
;         const int s = sg + s4;
;         const f32x2* a2 = (const f32x2*)(Al + s * 64 + cg * 8);
;         const f32x2* w2 = (const f32x2*)(Wl + s * 64 + cg * 8);
;         const f32x2* b2 = (const f32x2*)(Bl + s * 64 + cg * 8);
;         const f32x2* k2 = (const f32x2*)(Kl + s * 64 + cg * 8);
;         const f32x2* r2 = (const f32x2*)(Rl + s * 64 + cg * 8);
;         f32x2 o[20];
; #pragma unroll
;         for (int i = 0; i < 4; ++i) { o[i] = a2[i]; o[4 + i] = w2[i]; o[8 + i] = b2[i]; o[12 + i] = k2[i]; o[16 + i] = r2[i]; }
;         const float vr = Vl[s * 64 + 32 * half + rp];
;         f32x2 p0 = St[0] * o[0], p1 = St[1] * o[1];
;         p0 = __builtin_elementwise_fma(St[2], o[2], p0); p1 = __builtin_elementwise_fma(St[3], o[3], p1);
;         const float sa = oct_sum((p0.x + p0.y) + (p1.x + p1.y));
;         const f32x2 sv = {sa, sa}, vv = {vr, vr};
;         f32x2 y0 = {0.f, 0.f}, y1 = {0.f, 0.f};
; #pragma unroll
;         for (int i = 0; i < 4; i += 2) {
;           St[i] = __builtin_elementwise_fma(St[i], o[4 + i], __builtin_elementwise_fma(sv, o[8 + i], vv * o[12 + i]));
;           St[i + 1] = __builtin_elementwise_fma(St[i + 1], o[5 + i], __builtin_elementwise_fma(sv, o[9 + i], vv * o[13 + i]));
;           y0 = __builtin_elementwise_fma(St[i], o[16 + i], y0);
;           y1 = __builtin_elementwise_fma(St[i + 1], o[17 + i], y1);
;         }
;         yy[s4] = oct_sum((y0.x + y0.y) + (y1.x + y1.y));
;       }
;       if (cg == 0) {
; #pragma unroll
;         for (int s4 = 0; s4 < 4; ++s4) Yl[(sg + s4) * 32 + rp] = yy[s4];
	v_pk_mul_f32 v[58:59], v[68:69], v[158:159] op_sel_hi:[1,0]
	v_pk_mul_f32 v[72:73], v[70:71], v[158:159] op_sel_hi:[1,0]
	ds_read_b128 v[68:71], v0 offset:8960
	v_add_f32_dpp v198, v198, v198 quad_perm:[1,0,3,2] row_mask:0xf bank_mask:0xf bound_ctrl:1
	v_add_f32_dpp v207, v207, v207 quad_perm:[1,0,3,2] row_mask:0xf bank_mask:0xf bound_ctrl:1
	v_pk_mul_f32 v[212:213], v[150:151], v[158:159] op_sel_hi:[1,0]
	v_add_f32_dpp v198, v198, v198 quad_perm:[2,3,0,1] row_mask:0xf bank_mask:0xf bound_ctrl:1
	v_add_f32_dpp v207, v207, v207 quad_perm:[2,3,0,1] row_mask:0xf bank_mask:0xf bound_ctrl:1
	v_pk_mul_f32 v[250:251], v[152:153], v[158:159] op_sel_hi:[1,0]
	ds_read_b128 v[150:153], v0 offset:8976
	v_add_f32_dpp v198, v198, v198 row_half_mirror row_mask:0xf bank_mask:0xf bound_ctrl:1
	v_add_f32_dpp v205, v207, v207 row_half_mirror row_mask:0xf bank_mask:0xf bound_ctrl:1
	ds_write_b32 v162, v205 offset:128
	s_waitcnt lgkmcnt(8)
	v_pk_fma_f32 v[58:59], v[198:199], v[50:51], v[58:59] op_sel_hi:[0,1,1]
	v_pk_fma_f32 v[72:73], v[198:199], v[52:53], v[72:73] op_sel_hi:[0,1,1]
	s_waitcnt lgkmcnt(6)
	v_pk_fma_f32 v[66:67], v[66:67], v[42:43], v[58:59]
	v_pk_fma_f32 v[64:65], v[64:65], v[44:45], v[72:73]
	v_pk_fma_f32 v[212:213], v[198:199], v[54:55], v[212:213] op_sel_hi:[0,1,1]
	v_pk_fma_f32 v[250:251], v[198:199], v[56:57], v[250:251] op_sel_hi:[0,1,1]
	v_pk_fma_f32 v[62:63], v[62:63], v[46:47], v[212:213]
	v_pk_fma_f32 v[60:61], v[60:61], v[48:49], v[250:251]
	ds_read_b128 v[50:53], v0 offset:21248
	ds_read_b128 v[54:57], v0 offset:21264
	ds_read_b128 v[42:45], v0 offset:4864
	ds_read_b128 v[46:49], v0 offset:4880
	s_waitcnt lgkmcnt(8)
	v_pk_fma_f32 v[58:59], v[66:67], v[154:155], 0 op_sel_hi:[1,1,0]
	v_pk_fma_f32 v[72:73], v[64:65], v[156:157], 0 op_sel_hi:[1,1,0]
	v_pk_fma_f32 v[58:59], v[62:63], v[246:247], v[58:59]
	v_pk_fma_f32 v[72:73], v[60:61], v[248:249], v[72:73]
	ds_read_b128 v[154:157], v0 offset:768
	ds_read_b128 v[246:249], v0 offset:784
	v_pk_add_f32 v[58:59], v[58:59], v[72:73]
	ds_read_b128 v[34:37], v0 offset:17408
	ds_read_b128 v[38:41], v0 offset:17424
	s_waitcnt lgkmcnt(10)
	v_pk_mul_f32 v[200:201], v[66:67], v[200:201]
	v_pk_mul_f32 v[202:203], v[64:65], v[202:203]
	v_pk_fma_f32 v[200:201], v[62:63], v[230:231], v[200:201]
	v_pk_fma_f32 v[202:203], v[60:61], v[232:233], v[202:203]
	v_pk_add_f32 v[200:201], v[200:201], v[202:203]
	v_add_f32_e32 v207, v58, v59
	v_add_f32_e32 v198, v200, v201
	s_waitcnt lgkmcnt(8)
	v_mov_b32_e32 v232, v159
	v_pk_mul_f32 v[58:59], v[68:69], v[232:233] op_sel_hi:[1,0]
	v_pk_mul_f32 v[72:73], v[70:71], v[232:233] op_sel_hi:[1,0]
	ds_read_b128 v[68:71], v0 offset:9216
	v_add_f32_dpp v198, v198, v198 quad_perm:[1,0,3,2] row_mask:0xf bank_mask:0xf bound_ctrl:1
	v_add_f32_dpp v207, v207, v207 quad_perm:[1,0,3,2] row_mask:0xf bank_mask:0xf bound_ctrl:1
	v_pk_mul_f32 v[212:213], v[150:151], v[232:233] op_sel_hi:[1,0]
	v_add_f32_dpp v198, v198, v198 quad_perm:[2,3,0,1] row_mask:0xf bank_mask:0xf bound_ctrl:1
	v_add_f32_dpp v207, v207, v207 quad_perm:[2,3,0,1] row_mask:0xf bank_mask:0xf bound_ctrl:1
	v_pk_mul_f32 v[250:251], v[152:153], v[232:233] op_sel_hi:[1,0]
	ds_read_b128 v[150:153], v0 offset:9232
	v_add_f32_dpp v198, v198, v198 row_half_mirror row_mask:0xf bank_mask:0xf bound_ctrl:1
	v_add_f32_dpp v163, v207, v207 row_half_mirror row_mask:0xf bank_mask:0xf bound_ctrl:1
	ds_read2st64_b32 v[158:159], v161 offset0:4 offset1:5
	ds_write_b32 v162, v163 offset:256
	s_waitcnt lgkmcnt(9)
	v_pk_fma_f32 v[58:59], v[198:199], v[50:51], v[58:59] op_sel_hi:[0,1,1]
	v_pk_fma_f32 v[72:73], v[198:199], v[52:53], v[72:73] op_sel_hi:[0,1,1]
	s_waitcnt lgkmcnt(7)
	v_pk_fma_f32 v[66:67], v[66:67], v[42:43], v[58:59]
	v_pk_fma_f32 v[64:65], v[64:65], v[44:45], v[72:73]
	v_pk_fma_f32 v[212:213], v[198:199], v[54:55], v[212:213] op_sel_hi:[0,1,1]
	v_pk_fma_f32 v[250:251], v[198:199], v[56:57], v[250:251] op_sel_hi:[0,1,1]
	v_pk_fma_f32 v[62:63], v[62:63], v[46:47], v[212:213]
	v_pk_fma_f32 v[60:61], v[60:61], v[48:49], v[250:251]
	ds_read_b128 v[50:53], v0 offset:21504
	ds_read_b128 v[54:57], v0 offset:21520
	ds_read_b128 v[42:45], v0 offset:5120
	ds_read_b128 v[46:49], v0 offset:5136
	s_waitcnt lgkmcnt(9)
	v_pk_fma_f32 v[58:59], v[66:67], v[154:155], 0 op_sel_hi:[1,1,0]
	v_pk_fma_f32 v[72:73], v[64:65], v[156:157], 0 op_sel_hi:[1,1,0]
	v_pk_fma_f32 v[58:59], v[62:63], v[246:247], v[58:59]
	v_pk_fma_f32 v[72:73], v[60:61], v[248:249], v[72:73]
	ds_read_b128 v[154:157], v0 offset:1024
	ds_read_b128 v[246:249], v0 offset:1040
	v_pk_add_f32 v[58:59], v[58:59], v[72:73]
	ds_read_b128 v[200:203], v0 offset:17664
	ds_read_b128 v[230:233], v0 offset:17680
	s_waitcnt lgkmcnt(11)
	v_pk_mul_f32 v[34:35], v[66:67], v[34:35]
	v_pk_mul_f32 v[36:37], v[64:65], v[36:37]
	v_pk_fma_f32 v[34:35], v[62:63], v[38:39], v[34:35]
	v_pk_fma_f32 v[36:37], v[60:61], v[40:41], v[36:37]
	v_pk_add_f32 v[34:35], v[34:35], v[36:37]
	v_add_f32_e32 v207, v58, v59
	v_add_f32_e32 v198, v34, v35
	s_waitcnt lgkmcnt(8)
	v_pk_mul_f32 v[58:59], v[68:69], v[158:159] op_sel_hi:[1,0]
	v_pk_mul_f32 v[72:73], v[70:71], v[158:159] op_sel_hi:[1,0]
	ds_read_b128 v[68:71], v0 offset:9472
	v_add_f32_dpp v198, v198, v198 quad_perm:[1,0,3,2] row_mask:0xf bank_mask:0xf bound_ctrl:1
	v_add_f32_dpp v207, v207, v207 quad_perm:[1,0,3,2] row_mask:0xf bank_mask:0xf bound_ctrl:1
	v_pk_mul_f32 v[212:213], v[150:151], v[158:159] op_sel_hi:[1,0]
	v_add_f32_dpp v198, v198, v198 quad_perm:[2,3,0,1] row_mask:0xf bank_mask:0xf bound_ctrl:1
	v_add_f32_dpp v207, v207, v207 quad_perm:[2,3,0,1] row_mask:0xf bank_mask:0xf bound_ctrl:1
	v_pk_mul_f32 v[250:251], v[152:153], v[158:159] op_sel_hi:[1,0]
	ds_read_b128 v[150:153], v0 offset:9488
	v_add_f32_dpp v198, v198, v198 row_half_mirror row_mask:0xf bank_mask:0xf bound_ctrl:1
	v_add_f32_dpp v205, v207, v207 row_half_mirror row_mask:0xf bank_mask:0xf bound_ctrl:1
	ds_write_b32 v162, v205 offset:384
	s_waitcnt lgkmcnt(8)
; DI float oct_sum(float v) { v += dpp_f<0xB1>(v); v += dpp_f<0x4E>(v); v += dpp_f<0x141>(v); return v; }
; DI void scan_item(const Params& p, int b, int h, int half, char* smem, unsigned* pgen, unsigned kp) {
;     ...
;       for (int s4 = 0; s4 < 4; ++s4) {
;         const int s = sg + s4;
;         const f32x2* a2 = (const f32x2*)(Al + s * 64 + cg * 8);
;         const f32x2* w2 = (const f32x2*)(Wl + s * 64 + cg * 8);
;         const f32x2* b2 = (const f32x2*)(Bl + s * 64 + cg * 8);
;         const f32x2* k2 = (const f32x2*)(Kl + s * 64 + cg * 8);
;         const f32x2* r2 = (const f32x2*)(Rl + s * 64 + cg * 8);
;         f32x2 o[20];
; #pragma unroll
;         for (int i = 0; i < 4; ++i) { o[i] = a2[i]; o[4 + i] = w2[i]; o[8 + i] = b2[i]; o[12 + i] = k2[i]; o[16 + i] = r2[i]; }
;         const float vr = Vl[s * 64 + 32 * half + rp];
;         f32x2 p0 = St[0] * o[0], p1 = St[1] * o[1];
;         p0 = __builtin_elementwise_fma(St[2], o[2], p0); p1 = __builtin_elementwise_fma(St[3], o[3], p1);
;         const float sa = oct_sum((p0.x + p0.y) + (p1.x + p1.y));
;         const f32x2 sv = {sa, sa}, vv = {vr, vr};
;         f32x2 y0 = {0.f, 0.f}, y1 = {0.f, 0.f};
; #pragma unroll
;         for (int i = 0; i < 4; i += 2) {
;           St[i] = __builtin_elementwise_fma(St[i], o[4 + i], __builtin_elementwise_fma(sv, o[8 + i], vv * o[12 + i]));
;           St[i + 1] = __builtin_elementwise_fma(St[i + 1], o[5 + i], __builtin_elementwise_fma(sv, o[9 + i], vv * o[13 + i]));
;           y0 = __builtin_elementwise_fma(St[i], o[16 + i], y0);
;           y1 = __builtin_elementwise_fma(St[i + 1], o[17 + i], y1);
;         }
;         yy[s4] = oct_sum((y0.x + y0.y) + (y1.x + y1.y));
;       }
;       if (cg == 0) {
; #pragma unroll
;         for (int s4 = 0; s4 < 4; ++s4) Yl[(sg + s4) * 32 + rp] = yy[s4];
	v_pk_fma_f32 v[58:59], v[198:199], v[50:51], v[58:59] op_sel_hi:[0,1,1]
	v_pk_fma_f32 v[72:73], v[198:199], v[52:53], v[72:73] op_sel_hi:[0,1,1]
	s_waitcnt lgkmcnt(6)
	v_pk_fma_f32 v[66:67], v[66:67], v[42:43], v[58:59]
	v_pk_fma_f32 v[64:65], v[64:65], v[44:45], v[72:73]
	v_pk_fma_f32 v[212:213], v[198:199], v[54:55], v[212:213] op_sel_hi:[0,1,1]
	v_pk_fma_f32 v[250:251], v[198:199], v[56:57], v[250:251] op_sel_hi:[0,1,1]
	v_pk_fma_f32 v[62:63], v[62:63], v[46:47], v[212:213]
	v_pk_fma_f32 v[60:61], v[60:61], v[48:49], v[250:251]
	ds_read_b128 v[50:53], v0 offset:21760
	ds_read_b128 v[54:57], v0 offset:21776
	ds_read_b128 v[42:45], v0 offset:5376
	ds_read_b128 v[46:49], v0 offset:5392
	s_waitcnt lgkmcnt(8)
	v_pk_fma_f32 v[58:59], v[66:67], v[154:155], 0 op_sel_hi:[1,1,0]
	v_pk_fma_f32 v[72:73], v[64:65], v[156:157], 0 op_sel_hi:[1,1,0]
	v_pk_fma_f32 v[58:59], v[62:63], v[246:247], v[58:59]
	v_pk_fma_f32 v[72:73], v[60:61], v[248:249], v[72:73]
	ds_read_b128 v[154:157], v0 offset:1280
	ds_read_b128 v[246:249], v0 offset:1296
	v_pk_add_f32 v[58:59], v[58:59], v[72:73]
	ds_read_b128 v[34:37], v0 offset:17920
	ds_read_b128 v[38:41], v0 offset:17936
	s_waitcnt lgkmcnt(10)
	v_pk_mul_f32 v[200:201], v[66:67], v[200:201]
	v_pk_mul_f32 v[202:203], v[64:65], v[202:203]
	v_pk_fma_f32 v[200:201], v[62:63], v[230:231], v[200:201]
	v_pk_fma_f32 v[202:203], v[60:61], v[232:233], v[202:203]
	v_pk_add_f32 v[200:201], v[200:201], v[202:203]
	v_add_f32_e32 v207, v58, v59
	v_add_f32_e32 v198, v200, v201
	s_waitcnt lgkmcnt(8)
	v_mov_b32_e32 v232, v159
	v_pk_mul_f32 v[58:59], v[68:69], v[232:233] op_sel_hi:[1,0]
	v_pk_mul_f32 v[72:73], v[70:71], v[232:233] op_sel_hi:[1,0]
	ds_read_b128 v[68:71], v0 offset:9728
	v_add_f32_dpp v198, v198, v198 quad_perm:[1,0,3,2] row_mask:0xf bank_mask:0xf bound_ctrl:1
	v_add_f32_dpp v207, v207, v207 quad_perm:[1,0,3,2] row_mask:0xf bank_mask:0xf bound_ctrl:1
	v_pk_mul_f32 v[212:213], v[150:151], v[232:233] op_sel_hi:[1,0]
	v_add_f32_dpp v198, v198, v198 quad_perm:[2,3,0,1] row_mask:0xf bank_mask:0xf bound_ctrl:1
	v_add_f32_dpp v207, v207, v207 quad_perm:[2,3,0,1] row_mask:0xf bank_mask:0xf bound_ctrl:1
	v_pk_mul_f32 v[250:251], v[152:153], v[232:233] op_sel_hi:[1,0]
	ds_read_b128 v[150:153], v0 offset:9744
	v_add_f32_dpp v198, v198, v198 row_half_mirror row_mask:0xf bank_mask:0xf bound_ctrl:1
	v_add_f32_dpp v163, v207, v207 row_half_mirror row_mask:0xf bank_mask:0xf bound_ctrl:1
	ds_read2st64_b32 v[158:159], v161 offset0:6 offset1:7
	ds_write_b32 v162, v163 offset:512
	s_waitcnt lgkmcnt(9)
	v_pk_fma_f32 v[58:59], v[198:199], v[50:51], v[58:59] op_sel_hi:[0,1,1]
	v_pk_fma_f32 v[72:73], v[198:199], v[52:53], v[72:73] op_sel_hi:[0,1,1]
	s_waitcnt lgkmcnt(7)
	v_pk_fma_f32 v[66:67], v[66:67], v[42:43], v[58:59]
	v_pk_fma_f32 v[64:65], v[64:65], v[44:45], v[72:73]
	v_pk_fma_f32 v[212:213], v[198:199], v[54:55], v[212:213] op_sel_hi:[0,1,1]
	v_pk_fma_f32 v[250:251], v[198:199], v[56:57], v[250:251] op_sel_hi:[0,1,1]
	v_pk_fma_f32 v[62:63], v[62:63], v[46:47], v[212:213]
	v_pk_fma_f32 v[60:61], v[60:61], v[48:49], v[250:251]
	ds_read_b128 v[50:53], v0 offset:22016
	ds_read_b128 v[54:57], v0 offset:22032
	ds_read_b128 v[42:45], v0 offset:5632
	ds_read_b128 v[46:49], v0 offset:5648
	s_waitcnt lgkmcnt(9)
	v_pk_fma_f32 v[58:59], v[66:67], v[154:155], 0 op_sel_hi:[1,1,0]
	v_pk_fma_f32 v[72:73], v[64:65], v[156:157], 0 op_sel_hi:[1,1,0]
	v_pk_fma_f32 v[58:59], v[62:63], v[246:247], v[58:59]
	v_pk_fma_f32 v[72:73], v[60:61], v[248:249], v[72:73]
	ds_read_b128 v[154:157], v0 offset:1536
	ds_read_b128 v[246:249], v0 offset:1552
	v_pk_add_f32 v[58:59], v[58:59], v[72:73]
	ds_read_b128 v[200:203], v0 offset:18176
	ds_read_b128 v[230:233], v0 offset:18192
	s_waitcnt lgkmcnt(11)
	v_pk_mul_f32 v[34:35], v[66:67], v[34:35]
	v_pk_mul_f32 v[36:37], v[64:65], v[36:37]
	v_pk_fma_f32 v[34:35], v[62:63], v[38:39], v[34:35]
	v_pk_fma_f32 v[36:37], v[60:61], v[40:41], v[36:37]
	v_pk_add_f32 v[34:35], v[34:35], v[36:37]
	v_add_f32_e32 v207, v58, v59
	v_add_f32_e32 v198, v34, v35
	s_waitcnt lgkmcnt(8)
	v_pk_mul_f32 v[58:59], v[68:69], v[158:159] op_sel_hi:[1,0]
	v_pk_mul_f32 v[72:73], v[70:71], v[158:159] op_sel_hi:[1,0]
	ds_read_b128 v[68:71], v0 offset:9984
	v_add_f32_dpp v198, v198, v198 quad_perm:[1,0,3,2] row_mask:0xf bank_mask:0xf bound_ctrl:1
	v_add_f32_dpp v207, v207, v207 quad_perm:[1,0,3,2] row_mask:0xf bank_mask:0xf bound_ctrl:1
	v_pk_mul_f32 v[212:213], v[150:151], v[158:159] op_sel_hi:[1,0]
	v_add_f32_dpp v198, v198, v198 quad_perm:[2,3,0,1] row_mask:0xf bank_mask:0xf bound_ctrl:1
	v_add_f32_dpp v207, v207, v207 quad_perm:[2,3,0,1] row_mask:0xf bank_mask:0xf bound_ctrl:1
	v_pk_mul_f32 v[250:251], v[152:153], v[158:159] op_sel_hi:[1,0]
	ds_read_b128 v[150:153], v0 offset:10000
	v_add_f32_dpp v198, v198, v198 row_half_mirror row_mask:0xf bank_mask:0xf bound_ctrl:1
	v_add_f32_dpp v205, v207, v207 row_half_mirror row_mask:0xf bank_mask:0xf bound_ctrl:1
	ds_write_b32 v162, v205 offset:640
	s_waitcnt lgkmcnt(8)
	v_pk_fma_f32 v[58:59], v[198:199], v[50:51], v[58:59] op_sel_hi:[0,1,1]
	v_pk_fma_f32 v[72:73], v[198:199], v[52:53], v[72:73] op_sel_hi:[0,1,1]
	s_waitcnt lgkmcnt(6)
	v_pk_fma_f32 v[66:67], v[66:67], v[42:43], v[58:59]
	v_pk_fma_f32 v[64:65], v[64:65], v[44:45], v[72:73]
	v_pk_fma_f32 v[212:213], v[198:199], v[54:55], v[212:213] op_sel_hi:[0,1,1]
	v_pk_fma_f32 v[250:251], v[198:199], v[56:57], v[250:251] op_sel_hi:[0,1,1]
	v_pk_fma_f32 v[62:63], v[62:63], v[46:47], v[212:213]
	v_pk_fma_f32 v[60:61], v[60:61], v[48:49], v[250:251]
	ds_read_b128 v[50:53], v0 offset:22272
	ds_read_b128 v[54:57], v0 offset:22288
	ds_read_b128 v[42:45], v0 offset:5888
	ds_read_b128 v[46:49], v0 offset:5904
	s_waitcnt lgkmcnt(8)
; DI float oct_sum(float v) { v += dpp_f<0xB1>(v); v += dpp_f<0x4E>(v); v += dpp_f<0x141>(v); return v; }
; DI void scan_item(const Params& p, int b, int h, int half, char* smem, unsigned* pgen, unsigned kp) {
;     ...
;       for (int s4 = 0; s4 < 4; ++s4) {
;         const int s = sg + s4;
;         const f32x2* a2 = (const f32x2*)(Al + s * 64 + cg * 8);
;         const f32x2* w2 = (const f32x2*)(Wl + s * 64 + cg * 8);
;         const f32x2* b2 = (const f32x2*)(Bl + s * 64 + cg * 8);
;         const f32x2* k2 = (const f32x2*)(Kl + s * 64 + cg * 8);
;         const f32x2* r2 = (const f32x2*)(Rl + s * 64 + cg * 8);
;         f32x2 o[20];
; #pragma unroll
;         for (int i = 0; i < 4; ++i) { o[i] = a2[i]; o[4 + i] = w2[i]; o[8 + i] = b2[i]; o[12 + i] = k2[i]; o[16 + i] = r2[i]; }
;         const float vr = Vl[s * 64 + 32 * half + rp];
;         f32x2 p0 = St[0] * o[0], p1 = St[1] * o[1];
;         p0 = __builtin_elementwise_fma(St[2], o[2], p0); p1 = __builtin_elementwise_fma(St[3], o[3], p1);
;         const float sa = oct_sum((p0.x + p0.y) + (p1.x + p1.y));
;         const f32x2 sv = {sa, sa}, vv = {vr, vr};
;         f32x2 y0 = {0.f, 0.f}, y1 = {0.f, 0.f};
; #pragma unroll
;         for (int i = 0; i < 4; i += 2) {
;           St[i] = __builtin_elementwise_fma(St[i], o[4 + i], __builtin_elementwise_fma(sv, o[8 + i], vv * o[12 + i]));
;           St[i + 1] = __builtin_elementwise_fma(St[i + 1], o[5 + i], __builtin_elementwise_fma(sv, o[9 + i], vv * o[13 + i]));
;           y0 = __builtin_elementwise_fma(St[i], o[16 + i], y0);
;           y1 = __builtin_elementwise_fma(St[i + 1], o[17 + i], y1);
;         }
;         yy[s4] = oct_sum((y0.x + y0.y) + (y1.x + y1.y));
;       }
;       if (cg == 0) {
; #pragma unroll
;         for (int s4 = 0; s4 < 4; ++s4) Yl[(sg + s4) * 32 + rp] = yy[s4];
	v_pk_fma_f32 v[58:59], v[66:67], v[154:155], 0 op_sel_hi:[1,1,0]
	v_pk_fma_f32 v[72:73], v[64:65], v[156:157], 0 op_sel_hi:[1,1,0]
	v_pk_fma_f32 v[58:59], v[62:63], v[246:247], v[58:59]
	v_pk_fma_f32 v[72:73], v[60:61], v[248:249], v[72:73]
	ds_read_b128 v[154:157], v0 offset:1792
	ds_read_b128 v[246:249], v0 offset:1808
	v_pk_add_f32 v[58:59], v[58:59], v[72:73]
	ds_read_b128 v[34:37], v0 offset:18432
	ds_read_b128 v[38:41], v0 offset:18448
	s_waitcnt lgkmcnt(10)
	v_pk_mul_f32 v[200:201], v[66:67], v[200:201]
	v_pk_mul_f32 v[202:203], v[64:65], v[202:203]
	v_pk_fma_f32 v[200:201], v[62:63], v[230:231], v[200:201]
	v_pk_fma_f32 v[202:203], v[60:61], v[232:233], v[202:203]
	v_pk_add_f32 v[200:201], v[200:201], v[202:203]
	v_add_f32_e32 v207, v58, v59
	v_add_f32_e32 v198, v200, v201
	s_waitcnt lgkmcnt(8)
	v_mov_b32_e32 v232, v159
	v_pk_mul_f32 v[58:59], v[68:69], v[232:233] op_sel_hi:[1,0]
	v_pk_mul_f32 v[72:73], v[70:71], v[232:233] op_sel_hi:[1,0]
	ds_read_b128 v[68:71], v0 offset:10240
	v_add_f32_dpp v198, v198, v198 quad_perm:[1,0,3,2] row_mask:0xf bank_mask:0xf bound_ctrl:1
	v_add_f32_dpp v207, v207, v207 quad_perm:[1,0,3,2] row_mask:0xf bank_mask:0xf bound_ctrl:1
	v_pk_mul_f32 v[212:213], v[150:151], v[232:233] op_sel_hi:[1,0]
	v_add_f32_dpp v198, v198, v198 quad_perm:[2,3,0,1] row_mask:0xf bank_mask:0xf bound_ctrl:1
	v_add_f32_dpp v207, v207, v207 quad_perm:[2,3,0,1] row_mask:0xf bank_mask:0xf bound_ctrl:1
	v_pk_mul_f32 v[250:251], v[152:153], v[232:233] op_sel_hi:[1,0]
	ds_read_b128 v[150:153], v0 offset:10256
	v_add_f32_dpp v198, v198, v198 row_half_mirror row_mask:0xf bank_mask:0xf bound_ctrl:1
	v_add_f32_dpp v163, v207, v207 row_half_mirror row_mask:0xf bank_mask:0xf bound_ctrl:1
	ds_read2st64_b32 v[158:159], v161 offset0:8 offset1:9
	ds_write_b32 v162, v163 offset:768
	s_waitcnt lgkmcnt(9)
	v_pk_fma_f32 v[58:59], v[198:199], v[50:51], v[58:59] op_sel_hi:[0,1,1]
	v_pk_fma_f32 v[72:73], v[198:199], v[52:53], v[72:73] op_sel_hi:[0,1,1]
	s_waitcnt lgkmcnt(7)
	v_pk_fma_f32 v[66:67], v[66:67], v[42:43], v[58:59]
	v_pk_fma_f32 v[64:65], v[64:65], v[44:45], v[72:73]
	v_pk_fma_f32 v[212:213], v[198:199], v[54:55], v[212:213] op_sel_hi:[0,1,1]
	v_pk_fma_f32 v[250:251], v[198:199], v[56:57], v[250:251] op_sel_hi:[0,1,1]
	v_pk_fma_f32 v[62:63], v[62:63], v[46:47], v[212:213]
	v_pk_fma_f32 v[60:61], v[60:61], v[48:49], v[250:251]
	ds_read_b128 v[50:53], v0 offset:22528
	ds_read_b128 v[54:57], v0 offset:22544
	ds_read_b128 v[42:45], v0 offset:6144
	ds_read_b128 v[46:49], v0 offset:6160
	s_waitcnt lgkmcnt(9)
	v_pk_fma_f32 v[58:59], v[66:67], v[154:155], 0 op_sel_hi:[1,1,0]
	v_pk_fma_f32 v[72:73], v[64:65], v[156:157], 0 op_sel_hi:[1,1,0]
	v_pk_fma_f32 v[58:59], v[62:63], v[246:247], v[58:59]
	v_pk_fma_f32 v[72:73], v[60:61], v[248:249], v[72:73]
	ds_read_b128 v[154:157], v0 offset:2048
	ds_read_b128 v[246:249], v0 offset:2064
	v_pk_add_f32 v[58:59], v[58:59], v[72:73]
	ds_read_b128 v[200:203], v0 offset:18688
	ds_read_b128 v[230:233], v0 offset:18704
	s_waitcnt lgkmcnt(11)
	v_pk_mul_f32 v[34:35], v[66:67], v[34:35]
	v_pk_mul_f32 v[36:37], v[64:65], v[36:37]
	v_pk_fma_f32 v[34:35], v[62:63], v[38:39], v[34:35]
	v_pk_fma_f32 v[36:37], v[60:61], v[40:41], v[36:37]
	v_pk_add_f32 v[34:35], v[34:35], v[36:37]
	v_add_f32_e32 v207, v58, v59
	v_add_f32_e32 v198, v34, v35
	s_waitcnt lgkmcnt(8)
	v_pk_mul_f32 v[58:59], v[68:69], v[158:159] op_sel_hi:[1,0]
	v_pk_mul_f32 v[72:73], v[70:71], v[158:159] op_sel_hi:[1,0]
	ds_read_b128 v[68:71], v0 offset:10496
	v_add_f32_dpp v198, v198, v198 quad_perm:[1,0,3,2] row_mask:0xf bank_mask:0xf bound_ctrl:1
	v_add_f32_dpp v207, v207, v207 quad_perm:[1,0,3,2] row_mask:0xf bank_mask:0xf bound_ctrl:1
	v_pk_mul_f32 v[212:213], v[150:151], v[158:159] op_sel_hi:[1,0]
	v_add_f32_dpp v198, v198, v198 quad_perm:[2,3,0,1] row_mask:0xf bank_mask:0xf bound_ctrl:1
	v_add_f32_dpp v207, v207, v207 quad_perm:[2,3,0,1] row_mask:0xf bank_mask:0xf bound_ctrl:1
	v_pk_mul_f32 v[250:251], v[152:153], v[158:159] op_sel_hi:[1,0]
	ds_read_b128 v[150:153], v0 offset:10512
	v_add_f32_dpp v198, v198, v198 row_half_mirror row_mask:0xf bank_mask:0xf bound_ctrl:1
	v_add_f32_dpp v205, v207, v207 row_half_mirror row_mask:0xf bank_mask:0xf bound_ctrl:1
	ds_write_b32 v162, v205 offset:896
	s_waitcnt lgkmcnt(8)
	v_pk_fma_f32 v[58:59], v[198:199], v[50:51], v[58:59] op_sel_hi:[0,1,1]
	v_pk_fma_f32 v[72:73], v[198:199], v[52:53], v[72:73] op_sel_hi:[0,1,1]
	s_waitcnt lgkmcnt(6)
	v_pk_fma_f32 v[66:67], v[66:67], v[42:43], v[58:59]
	v_pk_fma_f32 v[64:65], v[64:65], v[44:45], v[72:73]
	v_pk_fma_f32 v[212:213], v[198:199], v[54:55], v[212:213] op_sel_hi:[0,1,1]
	v_pk_fma_f32 v[250:251], v[198:199], v[56:57], v[250:251] op_sel_hi:[0,1,1]
	v_pk_fma_f32 v[62:63], v[62:63], v[46:47], v[212:213]
	v_pk_fma_f32 v[60:61], v[60:61], v[48:49], v[250:251]
	ds_read_b128 v[50:53], v0 offset:22784
	ds_read_b128 v[54:57], v0 offset:22800
	ds_read_b128 v[42:45], v0 offset:6400
	ds_read_b128 v[46:49], v0 offset:6416
	s_waitcnt lgkmcnt(8)
	v_pk_fma_f32 v[58:59], v[66:67], v[154:155], 0 op_sel_hi:[1,1,0]
	v_pk_fma_f32 v[72:73], v[64:65], v[156:157], 0 op_sel_hi:[1,1,0]
	v_pk_fma_f32 v[58:59], v[62:63], v[246:247], v[58:59]
	v_pk_fma_f32 v[72:73], v[60:61], v[248:249], v[72:73]
	ds_read_b128 v[154:157], v0 offset:2304
	ds_read_b128 v[246:249], v0 offset:2320
	v_pk_add_f32 v[58:59], v[58:59], v[72:73]
	ds_read_b128 v[34:37], v0 offset:18944
	ds_read_b128 v[38:41], v0 offset:18960
	s_waitcnt lgkmcnt(10)
	v_pk_mul_f32 v[200:201], v[66:67], v[200:201]
	v_pk_mul_f32 v[202:203], v[64:65], v[202:203]
	v_pk_fma_f32 v[200:201], v[62:63], v[230:231], v[200:201]
	v_pk_fma_f32 v[202:203], v[60:61], v[232:233], v[202:203]
	v_pk_add_f32 v[200:201], v[200:201], v[202:203]
	v_add_f32_e32 v207, v58, v59
	v_add_f32_e32 v198, v200, v201
	s_waitcnt lgkmcnt(8)
; DI float oct_sum(float v) { v += dpp_f<0xB1>(v); v += dpp_f<0x4E>(v); v += dpp_f<0x141>(v); return v; }
; DI void scan_item(const Params& p, int b, int h, int half, char* smem, unsigned* pgen, unsigned kp) {
;     ...
;       for (int s4 = 0; s4 < 4; ++s4) {
;         const int s = sg + s4;
;         const f32x2* a2 = (const f32x2*)(Al + s * 64 + cg * 8);
;         const f32x2* w2 = (const f32x2*)(Wl + s * 64 + cg * 8);
;         const f32x2* b2 = (const f32x2*)(Bl + s * 64 + cg * 8);
;         const f32x2* k2 = (const f32x2*)(Kl + s * 64 + cg * 8);
;         const f32x2* r2 = (const f32x2*)(Rl + s * 64 + cg * 8);
;         f32x2 o[20];
; #pragma unroll
;         for (int i = 0; i < 4; ++i) { o[i] = a2[i]; o[4 + i] = w2[i]; o[8 + i] = b2[i]; o[12 + i] = k2[i]; o[16 + i] = r2[i]; }
;         const float vr = Vl[s * 64 + 32 * half + rp];
;         f32x2 p0 = St[0] * o[0], p1 = St[1] * o[1];
;         p0 = __builtin_elementwise_fma(St[2], o[2], p0); p1 = __builtin_elementwise_fma(St[3], o[3], p1);
;         const float sa = oct_sum((p0.x + p0.y) + (p1.x + p1.y));
;         const f32x2 sv = {sa, sa}, vv = {vr, vr};
;         f32x2 y0 = {0.f, 0.f}, y1 = {0.f, 0.f};
; #pragma unroll
;         for (int i = 0; i < 4; i += 2) {
;           St[i] = __builtin_elementwise_fma(St[i], o[4 + i], __builtin_elementwise_fma(sv, o[8 + i], vv * o[12 + i]));
;           St[i + 1] = __builtin_elementwise_fma(St[i + 1], o[5 + i], __builtin_elementwise_fma(sv, o[9 + i], vv * o[13 + i]));
;           y0 = __builtin_elementwise_fma(St[i], o[16 + i], y0);
;           y1 = __builtin_elementwise_fma(St[i + 1], o[17 + i], y1);
;         }
;         yy[s4] = oct_sum((y0.x + y0.y) + (y1.x + y1.y));
;       }
;       if (cg == 0) {
; #pragma unroll
;         for (int s4 = 0; s4 < 4; ++s4) Yl[(sg + s4) * 32 + rp] = yy[s4];
	v_mov_b32_e32 v232, v159
	v_pk_mul_f32 v[58:59], v[68:69], v[232:233] op_sel_hi:[1,0]
	v_pk_mul_f32 v[72:73], v[70:71], v[232:233] op_sel_hi:[1,0]
	ds_read_b128 v[68:71], v0 offset:10752
	v_add_f32_dpp v198, v198, v198 quad_perm:[1,0,3,2] row_mask:0xf bank_mask:0xf bound_ctrl:1
	v_add_f32_dpp v207, v207, v207 quad_perm:[1,0,3,2] row_mask:0xf bank_mask:0xf bound_ctrl:1
	v_pk_mul_f32 v[212:213], v[150:151], v[232:233] op_sel_hi:[1,0]
	v_add_f32_dpp v198, v198, v198 quad_perm:[2,3,0,1] row_mask:0xf bank_mask:0xf bound_ctrl:1
	v_add_f32_dpp v207, v207, v207 quad_perm:[2,3,0,1] row_mask:0xf bank_mask:0xf bound_ctrl:1
	v_pk_mul_f32 v[250:251], v[152:153], v[232:233] op_sel_hi:[1,0]
	ds_read_b128 v[150:153], v0 offset:10768
	v_add_f32_dpp v198, v198, v198 row_half_mirror row_mask:0xf bank_mask:0xf bound_ctrl:1
	v_add_f32_dpp v163, v207, v207 row_half_mirror row_mask:0xf bank_mask:0xf bound_ctrl:1
	ds_read2st64_b32 v[158:159], v161 offset0:10 offset1:11
	ds_write_b32 v162, v163 offset:1024
	s_waitcnt lgkmcnt(9)
	v_pk_fma_f32 v[58:59], v[198:199], v[50:51], v[58:59] op_sel_hi:[0,1,1]
	v_pk_fma_f32 v[72:73], v[198:199], v[52:53], v[72:73] op_sel_hi:[0,1,1]
	s_waitcnt lgkmcnt(7)
	v_pk_fma_f32 v[66:67], v[66:67], v[42:43], v[58:59]
	v_pk_fma_f32 v[64:65], v[64:65], v[44:45], v[72:73]
	v_pk_fma_f32 v[212:213], v[198:199], v[54:55], v[212:213] op_sel_hi:[0,1,1]
	v_pk_fma_f32 v[250:251], v[198:199], v[56:57], v[250:251] op_sel_hi:[0,1,1]
	v_pk_fma_f32 v[62:63], v[62:63], v[46:47], v[212:213]
	v_pk_fma_f32 v[60:61], v[60:61], v[48:49], v[250:251]
	ds_read_b128 v[50:53], v0 offset:23040
	ds_read_b128 v[54:57], v0 offset:23056
	ds_read_b128 v[42:45], v0 offset:6656
	ds_read_b128 v[46:49], v0 offset:6672
	s_waitcnt lgkmcnt(9)
	v_pk_fma_f32 v[58:59], v[66:67], v[154:155], 0 op_sel_hi:[1,1,0]
	v_pk_fma_f32 v[72:73], v[64:65], v[156:157], 0 op_sel_hi:[1,1,0]
	v_pk_fma_f32 v[58:59], v[62:63], v[246:247], v[58:59]
	v_pk_fma_f32 v[72:73], v[60:61], v[248:249], v[72:73]
	ds_read_b128 v[154:157], v0 offset:2560
	ds_read_b128 v[246:249], v0 offset:2576
	v_pk_add_f32 v[58:59], v[58:59], v[72:73]
	ds_read_b128 v[200:203], v0 offset:19200
	ds_read_b128 v[230:233], v0 offset:19216
	s_waitcnt lgkmcnt(11)
	v_pk_mul_f32 v[34:35], v[66:67], v[34:35]
	v_pk_mul_f32 v[36:37], v[64:65], v[36:37]
	v_pk_fma_f32 v[34:35], v[62:63], v[38:39], v[34:35]
	v_pk_fma_f32 v[36:37], v[60:61], v[40:41], v[36:37]
	v_pk_add_f32 v[34:35], v[34:35], v[36:37]
	v_add_f32_e32 v207, v58, v59
	v_add_f32_e32 v198, v34, v35
	s_waitcnt lgkmcnt(8)
	v_pk_mul_f32 v[58:59], v[68:69], v[158:159] op_sel_hi:[1,0]
	v_pk_mul_f32 v[72:73], v[70:71], v[158:159] op_sel_hi:[1,0]
	ds_read_b128 v[68:71], v0 offset:11008
	v_add_f32_dpp v198, v198, v198 quad_perm:[1,0,3,2] row_mask:0xf bank_mask:0xf bound_ctrl:1
	v_add_f32_dpp v207, v207, v207 quad_perm:[1,0,3,2] row_mask:0xf bank_mask:0xf bound_ctrl:1
	v_pk_mul_f32 v[212:213], v[150:151], v[158:159] op_sel_hi:[1,0]
	v_add_f32_dpp v198, v198, v198 quad_perm:[2,3,0,1] row_mask:0xf bank_mask:0xf bound_ctrl:1
	v_add_f32_dpp v207, v207, v207 quad_perm:[2,3,0,1] row_mask:0xf bank_mask:0xf bound_ctrl:1
	v_pk_mul_f32 v[250:251], v[152:153], v[158:159] op_sel_hi:[1,0]
	ds_read_b128 v[150:153], v0 offset:11024
	v_add_f32_dpp v198, v198, v198 row_half_mirror row_mask:0xf bank_mask:0xf bound_ctrl:1
	v_add_f32_dpp v205, v207, v207 row_half_mirror row_mask:0xf bank_mask:0xf bound_ctrl:1
	ds_write_b32 v162, v205 offset:1152
	s_waitcnt lgkmcnt(8)
	v_pk_fma_f32 v[58:59], v[198:199], v[50:51], v[58:59] op_sel_hi:[0,1,1]
	v_pk_fma_f32 v[72:73], v[198:199], v[52:53], v[72:73] op_sel_hi:[0,1,1]
	s_waitcnt lgkmcnt(6)
	v_pk_fma_f32 v[66:67], v[66:67], v[42:43], v[58:59]
	v_pk_fma_f32 v[64:65], v[64:65], v[44:45], v[72:73]
	v_pk_fma_f32 v[212:213], v[198:199], v[54:55], v[212:213] op_sel_hi:[0,1,1]
	v_pk_fma_f32 v[250:251], v[198:199], v[56:57], v[250:251] op_sel_hi:[0,1,1]
	v_pk_fma_f32 v[62:63], v[62:63], v[46:47], v[212:213]
	v_pk_fma_f32 v[60:61], v[60:61], v[48:49], v[250:251]
	ds_read_b128 v[50:53], v0 offset:23296
	ds_read_b128 v[54:57], v0 offset:23312
	ds_read_b128 v[42:45], v0 offset:6912
	ds_read_b128 v[46:49], v0 offset:6928
	s_waitcnt lgkmcnt(8)
	v_pk_fma_f32 v[58:59], v[66:67], v[154:155], 0 op_sel_hi:[1,1,0]
	v_pk_fma_f32 v[72:73], v[64:65], v[156:157], 0 op_sel_hi:[1,1,0]
	v_pk_fma_f32 v[58:59], v[62:63], v[246:247], v[58:59]
	v_pk_fma_f32 v[72:73], v[60:61], v[248:249], v[72:73]
	ds_read_b128 v[154:157], v0 offset:2816
	ds_read_b128 v[246:249], v0 offset:2832
	v_pk_add_f32 v[58:59], v[58:59], v[72:73]
	ds_read_b128 v[34:37], v0 offset:19456
	ds_read_b128 v[38:41], v0 offset:19472
	s_waitcnt lgkmcnt(10)
	v_pk_mul_f32 v[200:201], v[66:67], v[200:201]
	v_pk_mul_f32 v[202:203], v[64:65], v[202:203]
	v_pk_fma_f32 v[200:201], v[62:63], v[230:231], v[200:201]
	v_pk_fma_f32 v[202:203], v[60:61], v[232:233], v[202:203]
	v_pk_add_f32 v[200:201], v[200:201], v[202:203]
	v_add_f32_e32 v207, v58, v59
	v_add_f32_e32 v198, v200, v201
	s_waitcnt lgkmcnt(8)
	v_mov_b32_e32 v232, v159
	v_pk_mul_f32 v[58:59], v[68:69], v[232:233] op_sel_hi:[1,0]
	v_pk_mul_f32 v[72:73], v[70:71], v[232:233] op_sel_hi:[1,0]
	ds_read_b128 v[68:71], v0 offset:11264
	v_add_f32_dpp v198, v198, v198 quad_perm:[1,0,3,2] row_mask:0xf bank_mask:0xf bound_ctrl:1
	v_add_f32_dpp v207, v207, v207 quad_perm:[1,0,3,2] row_mask:0xf bank_mask:0xf bound_ctrl:1
	v_pk_mul_f32 v[212:213], v[150:151], v[232:233] op_sel_hi:[1,0]
	v_add_f32_dpp v198, v198, v198 quad_perm:[2,3,0,1] row_mask:0xf bank_mask:0xf bound_ctrl:1
	v_add_f32_dpp v207, v207, v207 quad_perm:[2,3,0,1] row_mask:0xf bank_mask:0xf bound_ctrl:1
	v_pk_mul_f32 v[250:251], v[152:153], v[232:233] op_sel_hi:[1,0]
	ds_read_b128 v[150:153], v0 offset:11280
	v_add_f32_dpp v198, v198, v198 row_half_mirror row_mask:0xf bank_mask:0xf bound_ctrl:1
	v_add_f32_dpp v163, v207, v207 row_half_mirror row_mask:0xf bank_mask:0xf bound_ctrl:1
	ds_read2st64_b32 v[158:159], v161 offset0:12 offset1:13
	ds_write_b32 v162, v163 offset:1280
	s_waitcnt lgkmcnt(9)
; DI float oct_sum(float v) { v += dpp_f<0xB1>(v); v += dpp_f<0x4E>(v); v += dpp_f<0x141>(v); return v; }
; DI void scan_item(const Params& p, int b, int h, int half, char* smem, unsigned* pgen, unsigned kp) {
;     ...
;       for (int s4 = 0; s4 < 4; ++s4) {
;         const int s = sg + s4;
;         const f32x2* a2 = (const f32x2*)(Al + s * 64 + cg * 8);
;         const f32x2* w2 = (const f32x2*)(Wl + s * 64 + cg * 8);
;         const f32x2* b2 = (const f32x2*)(Bl + s * 64 + cg * 8);
;         const f32x2* k2 = (const f32x2*)(Kl + s * 64 + cg * 8);
;         const f32x2* r2 = (const f32x2*)(Rl + s * 64 + cg * 8);
;         f32x2 o[20];
; #pragma unroll
;         for (int i = 0; i < 4; ++i) { o[i] = a2[i]; o[4 + i] = w2[i]; o[8 + i] = b2[i]; o[12 + i] = k2[i]; o[16 + i] = r2[i]; }
;         const float vr = Vl[s * 64 + 32 * half + rp];
;         f32x2 p0 = St[0] * o[0], p1 = St[1] * o[1];
;         p0 = __builtin_elementwise_fma(St[2], o[2], p0); p1 = __builtin_elementwise_fma(St[3], o[3], p1);
;         const float sa = oct_sum((p0.x + p0.y) + (p1.x + p1.y));
;         const f32x2 sv = {sa, sa}, vv = {vr, vr};
;         f32x2 y0 = {0.f, 0.f}, y1 = {0.f, 0.f};
; #pragma unroll
;         for (int i = 0; i < 4; i += 2) {
;           St[i] = __builtin_elementwise_fma(St[i], o[4 + i], __builtin_elementwise_fma(sv, o[8 + i], vv * o[12 + i]));
;           St[i + 1] = __builtin_elementwise_fma(St[i + 1], o[5 + i], __builtin_elementwise_fma(sv, o[9 + i], vv * o[13 + i]));
;           y0 = __builtin_elementwise_fma(St[i], o[16 + i], y0);
;           y1 = __builtin_elementwise_fma(St[i + 1], o[17 + i], y1);
;         }
;         yy[s4] = oct_sum((y0.x + y0.y) + (y1.x + y1.y));
;       }
;       if (cg == 0) {
; #pragma unroll
;         for (int s4 = 0; s4 < 4; ++s4) Yl[(sg + s4) * 32 + rp] = yy[s4];
	v_pk_fma_f32 v[58:59], v[198:199], v[50:51], v[58:59] op_sel_hi:[0,1,1]
	v_pk_fma_f32 v[72:73], v[198:199], v[52:53], v[72:73] op_sel_hi:[0,1,1]
	s_waitcnt lgkmcnt(7)
	v_pk_fma_f32 v[66:67], v[66:67], v[42:43], v[58:59]
	v_pk_fma_f32 v[64:65], v[64:65], v[44:45], v[72:73]
	v_pk_fma_f32 v[212:213], v[198:199], v[54:55], v[212:213] op_sel_hi:[0,1,1]
	v_pk_fma_f32 v[250:251], v[198:199], v[56:57], v[250:251] op_sel_hi:[0,1,1]
	v_pk_fma_f32 v[62:63], v[62:63], v[46:47], v[212:213]
	v_pk_fma_f32 v[60:61], v[60:61], v[48:49], v[250:251]
	ds_read_b128 v[50:53], v0 offset:23552
	ds_read_b128 v[54:57], v0 offset:23568
	ds_read_b128 v[42:45], v0 offset:7168
	ds_read_b128 v[46:49], v0 offset:7184
	s_waitcnt lgkmcnt(9)
	v_pk_fma_f32 v[58:59], v[66:67], v[154:155], 0 op_sel_hi:[1,1,0]
	v_pk_fma_f32 v[72:73], v[64:65], v[156:157], 0 op_sel_hi:[1,1,0]
	v_pk_fma_f32 v[58:59], v[62:63], v[246:247], v[58:59]
	v_pk_fma_f32 v[72:73], v[60:61], v[248:249], v[72:73]
	ds_read_b128 v[154:157], v0 offset:3072
	ds_read_b128 v[246:249], v0 offset:3088
	v_pk_add_f32 v[58:59], v[58:59], v[72:73]
	ds_read_b128 v[200:203], v0 offset:19712
	ds_read_b128 v[230:233], v0 offset:19728
	s_waitcnt lgkmcnt(11)
	v_pk_mul_f32 v[34:35], v[66:67], v[34:35]
	v_pk_mul_f32 v[36:37], v[64:65], v[36:37]
	v_pk_fma_f32 v[34:35], v[62:63], v[38:39], v[34:35]
	v_pk_fma_f32 v[36:37], v[60:61], v[40:41], v[36:37]
	v_pk_add_f32 v[34:35], v[34:35], v[36:37]
	v_add_f32_e32 v207, v58, v59
	v_add_f32_e32 v198, v34, v35
	s_waitcnt lgkmcnt(8)
	v_pk_mul_f32 v[58:59], v[68:69], v[158:159] op_sel_hi:[1,0]
	v_pk_mul_f32 v[72:73], v[70:71], v[158:159] op_sel_hi:[1,0]
	ds_read_b128 v[68:71], v0 offset:11520
	v_add_f32_dpp v198, v198, v198 quad_perm:[1,0,3,2] row_mask:0xf bank_mask:0xf bound_ctrl:1
	v_add_f32_dpp v207, v207, v207 quad_perm:[1,0,3,2] row_mask:0xf bank_mask:0xf bound_ctrl:1
	v_pk_mul_f32 v[212:213], v[150:151], v[158:159] op_sel_hi:[1,0]
	v_add_f32_dpp v198, v198, v198 quad_perm:[2,3,0,1] row_mask:0xf bank_mask:0xf bound_ctrl:1
	v_add_f32_dpp v207, v207, v207 quad_perm:[2,3,0,1] row_mask:0xf bank_mask:0xf bound_ctrl:1
	v_pk_mul_f32 v[250:251], v[152:153], v[158:159] op_sel_hi:[1,0]
	ds_read_b128 v[150:153], v0 offset:11536
	v_add_f32_dpp v198, v198, v198 row_half_mirror row_mask:0xf bank_mask:0xf bound_ctrl:1
	v_add_f32_dpp v205, v207, v207 row_half_mirror row_mask:0xf bank_mask:0xf bound_ctrl:1
	ds_write_b32 v162, v205 offset:1408
	s_waitcnt lgkmcnt(8)
	v_pk_fma_f32 v[58:59], v[198:199], v[50:51], v[58:59] op_sel_hi:[0,1,1]
	v_pk_fma_f32 v[72:73], v[198:199], v[52:53], v[72:73] op_sel_hi:[0,1,1]
	s_waitcnt lgkmcnt(6)
	v_pk_fma_f32 v[66:67], v[66:67], v[42:43], v[58:59]
	v_pk_fma_f32 v[64:65], v[64:65], v[44:45], v[72:73]
	v_pk_fma_f32 v[212:213], v[198:199], v[54:55], v[212:213] op_sel_hi:[0,1,1]
	v_pk_fma_f32 v[250:251], v[198:199], v[56:57], v[250:251] op_sel_hi:[0,1,1]
	v_pk_fma_f32 v[62:63], v[62:63], v[46:47], v[212:213]
	v_pk_fma_f32 v[60:61], v[60:61], v[48:49], v[250:251]
	ds_read_b128 v[50:53], v0 offset:23808
	ds_read_b128 v[54:57], v0 offset:23824
	ds_read_b128 v[42:45], v0 offset:7424
	ds_read_b128 v[46:49], v0 offset:7440
	s_waitcnt lgkmcnt(8)
	v_pk_fma_f32 v[58:59], v[66:67], v[154:155], 0 op_sel_hi:[1,1,0]
	v_pk_fma_f32 v[72:73], v[64:65], v[156:157], 0 op_sel_hi:[1,1,0]
	v_pk_fma_f32 v[58:59], v[62:63], v[246:247], v[58:59]
	v_pk_fma_f32 v[72:73], v[60:61], v[248:249], v[72:73]
	ds_read_b128 v[154:157], v0 offset:3328
	ds_read_b128 v[246:249], v0 offset:3344
	v_pk_add_f32 v[58:59], v[58:59], v[72:73]
	ds_read_b128 v[34:37], v0 offset:19968
	ds_read_b128 v[38:41], v0 offset:19984
	s_waitcnt lgkmcnt(10)
	v_pk_mul_f32 v[200:201], v[66:67], v[200:201]
	v_pk_mul_f32 v[202:203], v[64:65], v[202:203]
	v_pk_fma_f32 v[200:201], v[62:63], v[230:231], v[200:201]
	v_pk_fma_f32 v[202:203], v[60:61], v[232:233], v[202:203]
	v_pk_add_f32 v[200:201], v[200:201], v[202:203]
	v_add_f32_e32 v207, v58, v59
	v_add_f32_e32 v198, v200, v201
	s_waitcnt lgkmcnt(8)
	v_mov_b32_e32 v232, v159
	v_pk_mul_f32 v[58:59], v[68:69], v[232:233] op_sel_hi:[1,0]
	v_pk_mul_f32 v[72:73], v[70:71], v[232:233] op_sel_hi:[1,0]
	ds_read_b128 v[68:71], v0 offset:11776
	v_add_f32_dpp v198, v198, v198 quad_perm:[1,0,3,2] row_mask:0xf bank_mask:0xf bound_ctrl:1
	v_add_f32_dpp v207, v207, v207 quad_perm:[1,0,3,2] row_mask:0xf bank_mask:0xf bound_ctrl:1
	v_pk_mul_f32 v[212:213], v[150:151], v[232:233] op_sel_hi:[1,0]
	v_add_f32_dpp v198, v198, v198 quad_perm:[2,3,0,1] row_mask:0xf bank_mask:0xf bound_ctrl:1
	v_add_f32_dpp v207, v207, v207 quad_perm:[2,3,0,1] row_mask:0xf bank_mask:0xf bound_ctrl:1
	v_pk_mul_f32 v[250:251], v[152:153], v[232:233] op_sel_hi:[1,0]
	ds_read_b128 v[150:153], v0 offset:11792
	v_add_f32_dpp v198, v198, v198 row_half_mirror row_mask:0xf bank_mask:0xf bound_ctrl:1
	v_add_f32_dpp v163, v207, v207 row_half_mirror row_mask:0xf bank_mask:0xf bound_ctrl:1
	ds_read2st64_b32 v[158:159], v161 offset0:14 offset1:15
	ds_write_b32 v162, v163 offset:1536
	s_waitcnt lgkmcnt(9)
	v_pk_fma_f32 v[58:59], v[198:199], v[50:51], v[58:59] op_sel_hi:[0,1,1]
	v_pk_fma_f32 v[72:73], v[198:199], v[52:53], v[72:73] op_sel_hi:[0,1,1]
	s_waitcnt lgkmcnt(7)
	v_pk_fma_f32 v[66:67], v[66:67], v[42:43], v[58:59]
	v_pk_fma_f32 v[64:65], v[64:65], v[44:45], v[72:73]
	v_pk_fma_f32 v[212:213], v[198:199], v[54:55], v[212:213] op_sel_hi:[0,1,1]
	v_pk_fma_f32 v[250:251], v[198:199], v[56:57], v[250:251] op_sel_hi:[0,1,1]
	v_pk_fma_f32 v[62:63], v[62:63], v[46:47], v[212:213]
	v_pk_fma_f32 v[60:61], v[60:61], v[48:49], v[250:251]
	ds_read_b128 v[50:53], v0 offset:24064
	ds_read_b128 v[54:57], v0 offset:24080
	ds_read_b128 v[42:45], v0 offset:7680
	ds_read_b128 v[46:49], v0 offset:7696
	s_waitcnt lgkmcnt(9)
; DI float oct_sum(float v) { v += dpp_f<0xB1>(v); v += dpp_f<0x4E>(v); v += dpp_f<0x141>(v); return v; }
; DI void scan_item(const Params& p, int b, int h, int half, char* smem, unsigned* pgen, unsigned kp) {
;     ...
;       for (int s4 = 0; s4 < 4; ++s4) {
;         const int s = sg + s4;
;         const f32x2* a2 = (const f32x2*)(Al + s * 64 + cg * 8);
;         const f32x2* w2 = (const f32x2*)(Wl + s * 64 + cg * 8);
;         const f32x2* b2 = (const f32x2*)(Bl + s * 64 + cg * 8);
;         const f32x2* k2 = (const f32x2*)(Kl + s * 64 + cg * 8);
;         const f32x2* r2 = (const f32x2*)(Rl + s * 64 + cg * 8);
;         f32x2 o[20];
; #pragma unroll
;         for (int i = 0; i < 4; ++i) { o[i] = a2[i]; o[4 + i] = w2[i]; o[8 + i] = b2[i]; o[12 + i] = k2[i]; o[16 + i] = r2[i]; }
;         const float vr = Vl[s * 64 + 32 * half + rp];
;         f32x2 p0 = St[0] * o[0], p1 = St[1] * o[1];
;         p0 = __builtin_elementwise_fma(St[2], o[2], p0); p1 = __builtin_elementwise_fma(St[3], o[3], p1);
;         const float sa = oct_sum((p0.x + p0.y) + (p1.x + p1.y));
;         const f32x2 sv = {sa, sa}, vv = {vr, vr};
;         f32x2 y0 = {0.f, 0.f}, y1 = {0.f, 0.f};
; #pragma unroll
;         for (int i = 0; i < 4; i += 2) {
;           St[i] = __builtin_elementwise_fma(St[i], o[4 + i], __builtin_elementwise_fma(sv, o[8 + i], vv * o[12 + i]));
;           St[i + 1] = __builtin_elementwise_fma(St[i + 1], o[5 + i], __builtin_elementwise_fma(sv, o[9 + i], vv * o[13 + i]));
;           y0 = __builtin_elementwise_fma(St[i], o[16 + i], y0);
;           y1 = __builtin_elementwise_fma(St[i + 1], o[17 + i], y1);
;         }
;         yy[s4] = oct_sum((y0.x + y0.y) + (y1.x + y1.y));
;       }
;       if (cg == 0) {
; #pragma unroll
;         for (int s4 = 0; s4 < 4; ++s4) Yl[(sg + s4) * 32 + rp] = yy[s4];
	v_pk_fma_f32 v[58:59], v[66:67], v[154:155], 0 op_sel_hi:[1,1,0]
	v_pk_fma_f32 v[72:73], v[64:65], v[156:157], 0 op_sel_hi:[1,1,0]
	v_pk_fma_f32 v[58:59], v[62:63], v[246:247], v[58:59]
	v_pk_fma_f32 v[72:73], v[60:61], v[248:249], v[72:73]
	ds_read_b128 v[154:157], v0 offset:3584
	ds_read_b128 v[246:249], v0 offset:3600
	v_pk_add_f32 v[58:59], v[58:59], v[72:73]
	ds_read_b128 v[200:203], v0 offset:20224
	ds_read_b128 v[230:233], v0 offset:20240
	s_waitcnt lgkmcnt(11)
	v_pk_mul_f32 v[34:35], v[66:67], v[34:35]
	v_pk_mul_f32 v[36:37], v[64:65], v[36:37]
	v_pk_fma_f32 v[34:35], v[62:63], v[38:39], v[34:35]
	v_pk_fma_f32 v[36:37], v[60:61], v[40:41], v[36:37]
	v_pk_add_f32 v[34:35], v[34:35], v[36:37]
	v_add_f32_e32 v207, v58, v59
	v_add_f32_e32 v198, v34, v35
	s_waitcnt lgkmcnt(8)
	v_pk_mul_f32 v[58:59], v[68:69], v[158:159] op_sel_hi:[1,0]
	v_pk_mul_f32 v[72:73], v[70:71], v[158:159] op_sel_hi:[1,0]
	ds_read_b128 v[68:71], v0 offset:12032
	v_add_f32_dpp v198, v198, v198 quad_perm:[1,0,3,2] row_mask:0xf bank_mask:0xf bound_ctrl:1
	v_add_f32_dpp v207, v207, v207 quad_perm:[1,0,3,2] row_mask:0xf bank_mask:0xf bound_ctrl:1
	v_pk_mul_f32 v[212:213], v[150:151], v[158:159] op_sel_hi:[1,0]
	v_add_f32_dpp v198, v198, v198 quad_perm:[2,3,0,1] row_mask:0xf bank_mask:0xf bound_ctrl:1
	v_add_f32_dpp v207, v207, v207 quad_perm:[2,3,0,1] row_mask:0xf bank_mask:0xf bound_ctrl:1
	v_pk_mul_f32 v[250:251], v[152:153], v[158:159] op_sel_hi:[1,0]
	ds_read_b128 v[150:153], v0 offset:12048
	v_add_f32_dpp v198, v198, v198 row_half_mirror row_mask:0xf bank_mask:0xf bound_ctrl:1
	v_add_f32_dpp v205, v207, v207 row_half_mirror row_mask:0xf bank_mask:0xf bound_ctrl:1
	ds_write_b32 v162, v205 offset:1664
	s_waitcnt lgkmcnt(8)
	v_pk_fma_f32 v[58:59], v[198:199], v[50:51], v[58:59] op_sel_hi:[0,1,1]
	v_pk_fma_f32 v[72:73], v[198:199], v[52:53], v[72:73] op_sel_hi:[0,1,1]
	s_waitcnt lgkmcnt(6)
	v_pk_fma_f32 v[66:67], v[66:67], v[42:43], v[58:59]
	v_pk_fma_f32 v[64:65], v[64:65], v[44:45], v[72:73]
	v_pk_fma_f32 v[212:213], v[198:199], v[54:55], v[212:213] op_sel_hi:[0,1,1]
	v_pk_fma_f32 v[250:251], v[198:199], v[56:57], v[250:251] op_sel_hi:[0,1,1]
	v_pk_fma_f32 v[62:63], v[62:63], v[46:47], v[212:213]
	v_pk_fma_f32 v[60:61], v[60:61], v[48:49], v[250:251]
	ds_read_b128 v[50:53], v0 offset:24320
	ds_read_b128 v[54:57], v0 offset:24336
	ds_read_b128 v[42:45], v0 offset:7936
	ds_read_b128 v[46:49], v0 offset:7952
	s_waitcnt lgkmcnt(8)
	v_pk_fma_f32 v[58:59], v[66:67], v[154:155], 0 op_sel_hi:[1,1,0]
	v_pk_fma_f32 v[72:73], v[64:65], v[156:157], 0 op_sel_hi:[1,1,0]
	v_pk_fma_f32 v[58:59], v[62:63], v[246:247], v[58:59]
	v_pk_fma_f32 v[72:73], v[60:61], v[248:249], v[72:73]
	ds_read_b128 v[154:157], v0 offset:3840
	ds_read_b128 v[246:249], v0 offset:3856
	v_pk_add_f32 v[58:59], v[58:59], v[72:73]
	s_waitcnt lgkmcnt(8)
	v_pk_mul_f32 v[200:201], v[66:67], v[200:201]
	v_pk_mul_f32 v[202:203], v[64:65], v[202:203]
	v_pk_fma_f32 v[200:201], v[62:63], v[230:231], v[200:201]
	v_pk_fma_f32 v[202:203], v[60:61], v[232:233], v[202:203]
	v_pk_add_f32 v[200:201], v[200:201], v[202:203]
	v_add_f32_e32 v207, v58, v59
	v_add_f32_e32 v198, v200, v201
	s_waitcnt lgkmcnt(6)
	v_mov_b32_e32 v232, v159
	v_pk_mul_f32 v[58:59], v[68:69], v[232:233] op_sel_hi:[1,0]
	v_pk_mul_f32 v[72:73], v[70:71], v[232:233] op_sel_hi:[1,0]
	v_add_f32_dpp v198, v198, v198 quad_perm:[1,0,3,2] row_mask:0xf bank_mask:0xf bound_ctrl:1
	v_add_f32_dpp v207, v207, v207 quad_perm:[1,0,3,2] row_mask:0xf bank_mask:0xf bound_ctrl:1
	v_pk_mul_f32 v[212:213], v[150:151], v[232:233] op_sel_hi:[1,0]
	v_add_f32_dpp v198, v198, v198 quad_perm:[2,3,0,1] row_mask:0xf bank_mask:0xf bound_ctrl:1
	v_add_f32_dpp v207, v207, v207 quad_perm:[2,3,0,1] row_mask:0xf bank_mask:0xf bound_ctrl:1
	v_pk_mul_f32 v[250:251], v[152:153], v[232:233] op_sel_hi:[1,0]
	v_add_f32_dpp v198, v198, v198 row_half_mirror row_mask:0xf bank_mask:0xf bound_ctrl:1
	v_add_f32_dpp v163, v207, v207 row_half_mirror row_mask:0xf bank_mask:0xf bound_ctrl:1
	ds_write_b32 v162, v163 offset:1792
	s_waitcnt lgkmcnt(4)
	v_pk_fma_f32 v[58:59], v[198:199], v[50:51], v[58:59] op_sel_hi:[0,1,1]
	v_pk_fma_f32 v[72:73], v[198:199], v[52:53], v[72:73] op_sel_hi:[0,1,1]
	s_waitcnt lgkmcnt(2)
	v_pk_fma_f32 v[66:67], v[66:67], v[42:43], v[58:59]
	v_pk_fma_f32 v[64:65], v[64:65], v[44:45], v[72:73]
	v_pk_fma_f32 v[212:213], v[198:199], v[54:55], v[212:213] op_sel_hi:[0,1,1]
	v_pk_fma_f32 v[250:251], v[198:199], v[56:57], v[250:251] op_sel_hi:[0,1,1]
	v_pk_fma_f32 v[62:63], v[62:63], v[46:47], v[212:213]
	v_pk_fma_f32 v[60:61], v[60:61], v[48:49], v[250:251]
	s_waitcnt lgkmcnt(0)
	v_pk_fma_f32 v[58:59], v[66:67], v[154:155], 0 op_sel_hi:[1,1,0]
	v_pk_fma_f32 v[72:73], v[64:65], v[156:157], 0 op_sel_hi:[1,1,0]
	v_pk_fma_f32 v[58:59], v[62:63], v[246:247], v[58:59]
	v_pk_fma_f32 v[72:73], v[60:61], v[248:249], v[72:73]
	v_pk_add_f32 v[58:59], v[58:59], v[72:73]
	s_nop 0
	v_add_f32_e32 v207, v58, v59
	s_nop 1
	v_add_f32_dpp v207, v207, v207 quad_perm:[1,0,3,2] row_mask:0xf bank_mask:0xf bound_ctrl:1
	s_nop 1
	v_add_f32_dpp v207, v207, v207 quad_perm:[2,3,0,1] row_mask:0xf bank_mask:0xf bound_ctrl:1
	s_nop 1
	v_add_f32_dpp v205, v207, v207 row_half_mirror row_mask:0xf bank_mask:0xf bound_ctrl:1
	ds_write_b32 v162, v205 offset:1920

; DI float oct_sum(float v) { v += dpp_f<0xB1>(v); v += dpp_f<0x4E>(v); v += dpp_f<0x141>(v); return v; }
; DI void scan_item(const Params& p, int b, int h, int half, char* smem, unsigned* pgen, unsigned kp) {
;     ...
;     for (int sg = 0; sg < SC; sg += 4) {
;       float yy[4];
; #pragma unroll
;       for (int s4 = 0; s4 < 4; ++s4) {
;         const int s = sg + s4;
;         const f32x2* a2 = (const f32x2*)(Al + s * 64 + cg * 8);
;         const f32x2* w2 = (const f32x2*)(Wl + s * 64 + cg * 8);
;         const f32x2* b2 = (const f32x2*)(Bl + s * 64 + cg * 8);
;         const f32x2* k2 = (const f32x2*)(Kl + s * 64 + cg * 8);
;         const f32x2* r2 = (const f32x2*)(Rl + s * 64 + cg * 8);
;         f32x2 o[20];
; #pragma unroll
;         for (int i = 0; i < 4; ++i) { o[i] = a2[i]; o[4 + i] = w2[i]; o[8 + i] = b2[i]; o[12 + i] = k2[i]; o[16 + i] = r2[i]; }
;         const float vr = Vl[s * 64 + 32 * half + rp];
;         f32x2 p0 = St[0] * o[0], p1 = St[1] * o[1];
;         p0 = __builtin_elementwise_fma(St[2], o[2], p0); p1 = __builtin_elementwise_fma(St[3], o[3], p1);
;         const float sa = oct_sum((p0.x + p0.y) + (p1.x + p1.y));
;         const f32x2 sv = {sa, sa}, vv = {vr, vr};
;         f32x2 y0 = {0.f, 0.f}, y1 = {0.f, 0.f};
; #pragma unroll
;         for (int i = 0; i < 4; i += 2) {
;           St[i] = __builtin_elementwise_fma(St[i], o[4 + i], __builtin_elementwise_fma(sv, o[8 + i], vv * o[12 + i]));
;           St[i + 1] = __builtin_elementwise_fma(St[i + 1], o[5 + i], __builtin_elementwise_fma(sv, o[9 + i], vv * o[13 + i]));
;           y0 = __builtin_elementwise_fma(St[i], o[16 + i], y0);
;           y1 = __builtin_elementwise_fma(St[i + 1], o[17 + i], y1);
;         }
;         yy[s4] = oct_sum((y0.x + y0.y) + (y1.x + y1.y));
;       }
;       if (cg == 0) {
; #pragma unroll
;         for (int s4 = 0; s4 < 4; ++s4) Yl[(sg + s4) * 32 + rp] = yy[s4];
.LBB0_711:
	s_mov_b32 s18, -4
	v_mov_b32_e32 v0, v214
	v_mov_b32_e32 v161, v160
	v_lshlrev_b32_e32 v162, 2, v173
	v_add_u32_e32 v162, 0xb000, v162
	v_cndmask_b32_e64 v162, v162, v225, s[12:13]
	ds_read_b128 v[34:37], v0 offset:16384
	ds_read_b128 v[38:41], v0 offset:16400
	ds_read_b128 v[68:71], v0 offset:8192
	ds_read_b128 v[150:153], v0 offset:8208
	ds_read2st64_b32 v[158:159], v161 offset0:0 offset1:1
	ds_read_b128 v[50:53], v0 offset:20480
	ds_read_b128 v[54:57], v0 offset:20496
	ds_read_b128 v[42:45], v0 offset:4096
	ds_read_b128 v[46:49], v0 offset:4112
	ds_read_b128 v[154:157], v0 offset:0
	ds_read_b128 v[246:249], v0 offset:16
	ds_read_b128 v[200:203], v0 offset:16640
	ds_read_b128 v[230:233], v0 offset:16656
	s_waitcnt lgkmcnt(11)
	v_pk_mul_f32 v[34:35], v[66:67], v[34:35]
	v_pk_mul_f32 v[36:37], v[64:65], v[36:37]
	v_pk_fma_f32 v[34:35], v[62:63], v[38:39], v[34:35]
	v_pk_fma_f32 v[36:37], v[60:61], v[40:41], v[36:37]
	v_pk_add_f32 v[34:35], v[34:35], v[36:37]
	v_add_f32_e32 v198, v34, v35
	s_waitcnt lgkmcnt(8)
	v_pk_mul_f32 v[58:59], v[68:69], v[158:159] op_sel_hi:[1,0]
	v_pk_mul_f32 v[72:73], v[70:71], v[158:159] op_sel_hi:[1,0]
	ds_read_b128 v[68:71], v0 offset:8448
	v_add_f32_dpp v198, v198, v198 quad_perm:[1,0,3,2] row_mask:0xf bank_mask:0xf bound_ctrl:1
	s_nop 0
	v_pk_mul_f32 v[212:213], v[150:151], v[158:159] op_sel_hi:[1,0]
	v_add_f32_dpp v198, v198, v198 quad_perm:[2,3,0,1] row_mask:0xf bank_mask:0xf bound_ctrl:1
	s_nop 0
	v_pk_mul_f32 v[250:251], v[152:153], v[158:159] op_sel_hi:[1,0]
	ds_read_b128 v[150:153], v0 offset:8464
	v_add_f32_dpp v198, v198, v198 row_half_mirror row_mask:0xf bank_mask:0xf bound_ctrl:1
	s_waitcnt lgkmcnt(8)
	v_pk_fma_f32 v[58:59], v[198:199], v[50:51], v[58:59] op_sel_hi:[0,1,1]
	v_pk_fma_f32 v[72:73], v[198:199], v[52:53], v[72:73] op_sel_hi:[0,1,1]
	s_waitcnt lgkmcnt(6)
	v_pk_fma_f32 v[66:67], v[66:67], v[42:43], v[58:59]
	v_pk_fma_f32 v[64:65], v[64:65], v[44:45], v[72:73]
	v_pk_fma_f32 v[212:213], v[198:199], v[54:55], v[212:213] op_sel_hi:[0,1,1]
	v_pk_fma_f32 v[250:251], v[198:199], v[56:57], v[250:251] op_sel_hi:[0,1,1]
	v_pk_fma_f32 v[62:63], v[62:63], v[46:47], v[212:213]
	v_pk_fma_f32 v[60:61], v[60:61], v[48:49], v[250:251]
	ds_read_b128 v[50:53], v0 offset:20736
	ds_read_b128 v[54:57], v0 offset:20752
	ds_read_b128 v[42:45], v0 offset:4352
	ds_read_b128 v[46:49], v0 offset:4368
	s_waitcnt lgkmcnt(8)
	v_pk_fma_f32 v[58:59], v[66:67], v[154:155], 0 op_sel_hi:[1,1,0]
	v_pk_fma_f32 v[72:73], v[64:65], v[156:157], 0 op_sel_hi:[1,1,0]
	v_pk_fma_f32 v[58:59], v[62:63], v[246:247], v[58:59]
	v_pk_fma_f32 v[72:73], v[60:61], v[248:249], v[72:73]
	ds_read_b128 v[154:157], v0 offset:256
	ds_read_b128 v[246:249], v0 offset:272
	v_pk_add_f32 v[58:59], v[58:59], v[72:73]
	ds_read_b128 v[34:37], v0 offset:16896
	ds_read_b128 v[38:41], v0 offset:16912
	s_waitcnt lgkmcnt(10)
	v_pk_mul_f32 v[200:201], v[66:67], v[200:201]
	v_pk_mul_f32 v[202:203], v[64:65], v[202:203]
	v_pk_fma_f32 v[200:201], v[62:63], v[230:231], v[200:201]
	v_pk_fma_f32 v[202:203], v[60:61], v[232:233], v[202:203]
	v_pk_add_f32 v[200:201], v[200:201], v[202:203]
	v_add_f32_e32 v207, v58, v59
	v_add_f32_e32 v198, v200, v201
	s_waitcnt lgkmcnt(8)
	v_mov_b32_e32 v232, v159
	v_pk_mul_f32 v[58:59], v[68:69], v[232:233] op_sel_hi:[1,0]
	v_pk_mul_f32 v[72:73], v[70:71], v[232:233] op_sel_hi:[1,0]
	ds_read_b128 v[68:71], v0 offset:8704
	v_add_f32_dpp v198, v198, v198 quad_perm:[1,0,3,2] row_mask:0xf bank_mask:0xf bound_ctrl:1
	v_add_f32_dpp v207, v207, v207 quad_perm:[1,0,3,2] row_mask:0xf bank_mask:0xf bound_ctrl:1
	v_pk_mul_f32 v[212:213], v[150:151], v[232:233] op_sel_hi:[1,0]
	v_add_f32_dpp v198, v198, v198 quad_perm:[2,3,0,1] row_mask:0xf bank_mask:0xf bound_ctrl:1
	v_add_f32_dpp v207, v207, v207 quad_perm:[2,3,0,1] row_mask:0xf bank_mask:0xf bound_ctrl:1
	v_pk_mul_f32 v[250:251], v[152:153], v[232:233] op_sel_hi:[1,0]
	ds_read_b128 v[150:153], v0 offset:8720
	v_add_f32_dpp v198, v198, v198 row_half_mirror row_mask:0xf bank_mask:0xf bound_ctrl:1
	v_add_f32_dpp v163, v207, v207 row_half_mirror row_mask:0xf bank_mask:0xf bound_ctrl:1
	ds_read2st64_b32 v[158:159], v161 offset0:2 offset1:3
	ds_write_b32 v162, v163 offset:0
	s_waitcnt lgkmcnt(9)
	v_pk_fma_f32 v[58:59], v[198:199], v[50:51], v[58:59] op_sel_hi:[0,1,1]
	v_pk_fma_f32 v[72:73], v[198:199], v[52:53], v[72:73] op_sel_hi:[0,1,1]
	s_waitcnt lgkmcnt(7)
	v_pk_fma_f32 v[66:67], v[66:67], v[42:43], v[58:59]
	v_pk_fma_f32 v[64:65], v[64:65], v[44:45], v[72:73]
	v_pk_fma_f32 v[212:213], v[198:199], v[54:55], v[212:213] op_sel_hi:[0,1,1]
	v_pk_fma_f32 v[250:251], v[198:199], v[56:57], v[250:251] op_sel_hi:[0,1,1]
	v_pk_fma_f32 v[62:63], v[62:63], v[46:47], v[212:213]
	v_pk_fma_f32 v[60:61], v[60:61], v[48:49], v[250:251]
	ds_read_b128 v[50:53], v0 offset:20992
	ds_read_b128 v[54:57], v0 offset:21008
	ds_read_b128 v[42:45], v0 offset:4608
	ds_read_b128 v[46:49], v0 offset:4624
	s_waitcnt lgkmcnt(9)
	v_pk_fma_f32 v[58:59], v[66:67], v[154:155], 0 op_sel_hi:[1,1,0]
	v_pk_fma_f32 v[72:73], v[64:65], v[156:157], 0 op_sel_hi:[1,1,0]
	v_pk_fma_f32 v[58:59], v[62:63], v[246:247], v[58:59]
	v_pk_fma_f32 v[72:73], v[60:61], v[248:249], v[72:73]
	ds_read_b128 v[154:157], v0 offset:512
	ds_read_b128 v[246:249], v0 offset:528
	v_pk_add_f32 v[58:59], v[58:59], v[72:73]
	ds_read_b128 v[200:203], v0 offset:17152
	ds_read_b128 v[230:233], v0 offset:17168
	s_waitcnt lgkmcnt(11)
	v_pk_mul_f32 v[34:35], v[66:67], v[34:35]
	v_pk_mul_f32 v[36:37], v[64:65], v[36:37]
	v_pk_fma_f32 v[34:35], v[62:63], v[38:39], v[34:35]
	v_pk_fma_f32 v[36:37], v[60:61], v[40:41], v[36:37]
	v_pk_add_f32 v[34:35], v[34:35], v[36:37]
	v_add_f32_e32 v207, v58, v59
	v_add_f32_e32 v198, v34, v35
	s_waitcnt lgkmcnt(8)
; DI float oct_sum(float v) { v += dpp_f<0xB1>(v); v += dpp_f<0x4E>(v); v += dpp_f<0x141>(v); return v; }
; DI void scan_item(const Params& p, int b, int h, int half, char* smem, unsigned* pgen, unsigned kp) {
;     ...
;       for (int s4 = 0; s4 < 4; ++s4) {
;         const int s = sg + s4;
;         const f32x2* a2 = (const f32x2*)(Al + s * 64 + cg * 8);
;         const f32x2* w2 = (const f32x2*)(Wl + s * 64 + cg * 8);
;         const f32x2* b2 = (const f32x2*)(Bl + s * 64 + cg * 8);
;         const f32x2* k2 = (const f32x2*)(Kl + s * 64 + cg * 8);
;         const f32x2* r2 = (const f32x2*)(Rl + s * 64 + cg * 8);
;         f32x2 o[20];
; #pragma unroll
;         for (int i = 0; i < 4; ++i) { o[i] = a2[i]; o[4 + i] = w2[i]; o[8 + i] = b2[i]; o[12 + i] = k2[i]; o[16 + i] = r2[i]; }
;         const float vr = Vl[s * 64 + 32 * half + rp];
;         f32x2 p0 = St[0] * o[0], p1 = St[1] * o[1];
;         p0 = __builtin_elementwise_fma(St[2], o[2], p0); p1 = __builtin_elementwise_fma(St[3], o[3], p1);
;         const float sa = oct_sum((p0.x + p0.y) + (p1.x + p1.y));
;         const f32x2 sv = {sa, sa}, vv = {vr, vr};
;         f32x2 y0 = {0.f, 0.f}, y1 = {0.f, 0.f};
; #pragma unroll
;         for (int i = 0; i < 4; i += 2) {
;           St[i] = __builtin_elementwise_fma(St[i], o[4 + i], __builtin_elementwise_fma(sv, o[8 + i], vv * o[12 + i]));
;           St[i + 1] = __builtin_elementwise_fma(St[i + 1], o[5 + i], __builtin_elementwise_fma(sv, o[9 + i], vv * o[13 + i]));
;           y0 = __builtin_elementwise_fma(St[i], o[16 + i], y0);
;           y1 = __builtin_elementwise_fma(St[i + 1], o[17 + i], y1);
;         }
;         yy[s4] = oct_sum((y0.x + y0.y) + (y1.x + y1.y));
;       }
;       if (cg == 0) {
; #pragma unroll
;         for (int s4 = 0; s4 < 4; ++s4) Yl[(sg + s4) * 32 + rp] = yy[s4];
	v_pk_mul_f32 v[58:59], v[68:69], v[158:159] op_sel_hi:[1,0]
	v_pk_mul_f32 v[72:73], v[70:71], v[158:159] op_sel_hi:[1,0]
	ds_read_b128 v[68:71], v0 offset:8960
	v_add_f32_dpp v198, v198, v198 quad_perm:[1,0,3,2] row_mask:0xf bank_mask:0xf bound_ctrl:1
	v_add_f32_dpp v207, v207, v207 quad_perm:[1,0,3,2] row_mask:0xf bank_mask:0xf bound_ctrl:1
	v_pk_mul_f32 v[212:213], v[150:151], v[158:159] op_sel_hi:[1,0]
	v_add_f32_dpp v198, v198, v198 quad_perm:[2,3,0,1] row_mask:0xf bank_mask:0xf bound_ctrl:1
	v_add_f32_dpp v207, v207, v207 quad_perm:[2,3,0,1] row_mask:0xf bank_mask:0xf bound_ctrl:1
	v_pk_mul_f32 v[250:251], v[152:153], v[158:159] op_sel_hi:[1,0]
	ds_read_b128 v[150:153], v0 offset:8976
	v_add_f32_dpp v198, v198, v198 row_half_mirror row_mask:0xf bank_mask:0xf bound_ctrl:1
	v_add_f32_dpp v205, v207, v207 row_half_mirror row_mask:0xf bank_mask:0xf bound_ctrl:1
	ds_write_b32 v162, v205 offset:128
	s_waitcnt lgkmcnt(8)
	v_pk_fma_f32 v[58:59], v[198:199], v[50:51], v[58:59] op_sel_hi:[0,1,1]
	v_pk_fma_f32 v[72:73], v[198:199], v[52:53], v[72:73] op_sel_hi:[0,1,1]
	s_waitcnt lgkmcnt(6)
	v_pk_fma_f32 v[66:67], v[66:67], v[42:43], v[58:59]
	v_pk_fma_f32 v[64:65], v[64:65], v[44:45], v[72:73]
	v_pk_fma_f32 v[212:213], v[198:199], v[54:55], v[212:213] op_sel_hi:[0,1,1]
	v_pk_fma_f32 v[250:251], v[198:199], v[56:57], v[250:251] op_sel_hi:[0,1,1]
	v_pk_fma_f32 v[62:63], v[62:63], v[46:47], v[212:213]
	v_pk_fma_f32 v[60:61], v[60:61], v[48:49], v[250:251]
	ds_read_b128 v[50:53], v0 offset:21248
	ds_read_b128 v[54:57], v0 offset:21264
	ds_read_b128 v[42:45], v0 offset:4864
	ds_read_b128 v[46:49], v0 offset:4880
	s_waitcnt lgkmcnt(8)
	v_pk_fma_f32 v[58:59], v[66:67], v[154:155], 0 op_sel_hi:[1,1,0]
	v_pk_fma_f32 v[72:73], v[64:65], v[156:157], 0 op_sel_hi:[1,1,0]
	v_pk_fma_f32 v[58:59], v[62:63], v[246:247], v[58:59]
	v_pk_fma_f32 v[72:73], v[60:61], v[248:249], v[72:73]
	ds_read_b128 v[154:157], v0 offset:768
	ds_read_b128 v[246:249], v0 offset:784
	v_pk_add_f32 v[58:59], v[58:59], v[72:73]
	ds_read_b128 v[34:37], v0 offset:17408
	ds_read_b128 v[38:41], v0 offset:17424
	s_waitcnt lgkmcnt(10)
	v_pk_mul_f32 v[200:201], v[66:67], v[200:201]
	v_pk_mul_f32 v[202:203], v[64:65], v[202:203]
	v_pk_fma_f32 v[200:201], v[62:63], v[230:231], v[200:201]
	v_pk_fma_f32 v[202:203], v[60:61], v[232:233], v[202:203]
	v_pk_add_f32 v[200:201], v[200:201], v[202:203]
	v_add_f32_e32 v207, v58, v59
	v_add_f32_e32 v198, v200, v201
	s_waitcnt lgkmcnt(8)
	v_mov_b32_e32 v232, v159
	v_pk_mul_f32 v[58:59], v[68:69], v[232:233] op_sel_hi:[1,0]
	v_pk_mul_f32 v[72:73], v[70:71], v[232:233] op_sel_hi:[1,0]
	ds_read_b128 v[68:71], v0 offset:9216
	v_add_f32_dpp v198, v198, v198 quad_perm:[1,0,3,2] row_mask:0xf bank_mask:0xf bound_ctrl:1
	v_add_f32_dpp v207, v207, v207 quad_perm:[1,0,3,2] row_mask:0xf bank_mask:0xf bound_ctrl:1
	v_pk_mul_f32 v[212:213], v[150:151], v[232:233] op_sel_hi:[1,0]
	v_add_f32_dpp v198, v198, v198 quad_perm:[2,3,0,1] row_mask:0xf bank_mask:0xf bound_ctrl:1
	v_add_f32_dpp v207, v207, v207 quad_perm:[2,3,0,1] row_mask:0xf bank_mask:0xf bound_ctrl:1
	v_pk_mul_f32 v[250:251], v[152:153], v[232:233] op_sel_hi:[1,0]
	ds_read_b128 v[150:153], v0 offset:9232
	v_add_f32_dpp v198, v198, v198 row_half_mirror row_mask:0xf bank_mask:0xf bound_ctrl:1
	v_add_f32_dpp v163, v207, v207 row_half_mirror row_mask:0xf bank_mask:0xf bound_ctrl:1
	ds_read2st64_b32 v[158:159], v161 offset0:4 offset1:5
	ds_write_b32 v162, v163 offset:256
	s_waitcnt lgkmcnt(9)
	v_pk_fma_f32 v[58:59], v[198:199], v[50:51], v[58:59] op_sel_hi:[0,1,1]
	v_pk_fma_f32 v[72:73], v[198:199], v[52:53], v[72:73] op_sel_hi:[0,1,1]
	s_waitcnt lgkmcnt(7)
	v_pk_fma_f32 v[66:67], v[66:67], v[42:43], v[58:59]
	v_pk_fma_f32 v[64:65], v[64:65], v[44:45], v[72:73]
	v_pk_fma_f32 v[212:213], v[198:199], v[54:55], v[212:213] op_sel_hi:[0,1,1]
	v_pk_fma_f32 v[250:251], v[198:199], v[56:57], v[250:251] op_sel_hi:[0,1,1]
	v_pk_fma_f32 v[62:63], v[62:63], v[46:47], v[212:213]
	v_pk_fma_f32 v[60:61], v[60:61], v[48:49], v[250:251]
	ds_read_b128 v[50:53], v0 offset:21504
	ds_read_b128 v[54:57], v0 offset:21520
	ds_read_b128 v[42:45], v0 offset:5120
	ds_read_b128 v[46:49], v0 offset:5136
	s_waitcnt lgkmcnt(9)
	v_pk_fma_f32 v[58:59], v[66:67], v[154:155], 0 op_sel_hi:[1,1,0]
	v_pk_fma_f32 v[72:73], v[64:65], v[156:157], 0 op_sel_hi:[1,1,0]
	v_pk_fma_f32 v[58:59], v[62:63], v[246:247], v[58:59]
	v_pk_fma_f32 v[72:73], v[60:61], v[248:249], v[72:73]
	ds_read_b128 v[154:157], v0 offset:1024
	ds_read_b128 v[246:249], v0 offset:1040
	v_pk_add_f32 v[58:59], v[58:59], v[72:73]
	ds_read_b128 v[200:203], v0 offset:17664
	ds_read_b128 v[230:233], v0 offset:17680
	s_waitcnt lgkmcnt(11)
	v_pk_mul_f32 v[34:35], v[66:67], v[34:35]
	v_pk_mul_f32 v[36:37], v[64:65], v[36:37]
	v_pk_fma_f32 v[34:35], v[62:63], v[38:39], v[34:35]
	v_pk_fma_f32 v[36:37], v[60:61], v[40:41], v[36:37]
	v_pk_add_f32 v[34:35], v[34:35], v[36:37]
	v_add_f32_e32 v207, v58, v59
	v_add_f32_e32 v198, v34, v35
	s_waitcnt lgkmcnt(8)
	v_pk_mul_f32 v[58:59], v[68:69], v[158:159] op_sel_hi:[1,0]
	v_pk_mul_f32 v[72:73], v[70:71], v[158:159] op_sel_hi:[1,0]
	ds_read_b128 v[68:71], v0 offset:9472
	v_add_f32_dpp v198, v198, v198 quad_perm:[1,0,3,2] row_mask:0xf bank_mask:0xf bound_ctrl:1
	v_add_f32_dpp v207, v207, v207 quad_perm:[1,0,3,2] row_mask:0xf bank_mask:0xf bound_ctrl:1
	v_pk_mul_f32 v[212:213], v[150:151], v[158:159] op_sel_hi:[1,0]
	v_add_f32_dpp v198, v198, v198 quad_perm:[2,3,0,1] row_mask:0xf bank_mask:0xf bound_ctrl:1
	v_add_f32_dpp v207, v207, v207 quad_perm:[2,3,0,1] row_mask:0xf bank_mask:0xf bound_ctrl:1
	v_pk_mul_f32 v[250:251], v[152:153], v[158:159] op_sel_hi:[1,0]
	ds_read_b128 v[150:153], v0 offset:9488
	v_add_f32_dpp v198, v198, v198 row_half_mirror row_mask:0xf bank_mask:0xf bound_ctrl:1
	v_add_f32_dpp v205, v207, v207 row_half_mirror row_mask:0xf bank_mask:0xf bound_ctrl:1
	ds_write_b32 v162, v205 offset:384
	s_waitcnt lgkmcnt(8)
; DI float oct_sum(float v) { v += dpp_f<0xB1>(v); v += dpp_f<0x4E>(v); v += dpp_f<0x141>(v); return v; }
; DI void scan_item(const Params& p, int b, int h, int half, char* smem, unsigned* pgen, unsigned kp) {
;     ...
;       for (int s4 = 0; s4 < 4; ++s4) {
;         const int s = sg + s4;
;         const f32x2* a2 = (const f32x2*)(Al + s * 64 + cg * 8);
;         const f32x2* w2 = (const f32x2*)(Wl + s * 64 + cg * 8);
;         const f32x2* b2 = (const f32x2*)(Bl + s * 64 + cg * 8);
;         const f32x2* k2 = (const f32x2*)(Kl + s * 64 + cg * 8);
;         const f32x2* r2 = (const f32x2*)(Rl + s * 64 + cg * 8);
;         f32x2 o[20];
; #pragma unroll
;         for (int i = 0; i < 4; ++i) { o[i] = a2[i]; o[4 + i] = w2[i]; o[8 + i] = b2[i]; o[12 + i] = k2[i]; o[16 + i] = r2[i]; }
;         const float vr = Vl[s * 64 + 32 * half + rp];
;         f32x2 p0 = St[0] * o[0], p1 = St[1] * o[1];
;         p0 = __builtin_elementwise_fma(St[2], o[2], p0); p1 = __builtin_elementwise_fma(St[3], o[3], p1);
;         const float sa = oct_sum((p0.x + p0.y) + (p1.x + p1.y));
;         const f32x2 sv = {sa, sa}, vv = {vr, vr};
;         f32x2 y0 = {0.f, 0.f}, y1 = {0.f, 0.f};
; #pragma unroll
;         for (int i = 0; i < 4; i += 2) {
;           St[i] = __builtin_elementwise_fma(St[i], o[4 + i], __builtin_elementwise_fma(sv, o[8 + i], vv * o[12 + i]));
;           St[i + 1] = __builtin_elementwise_fma(St[i + 1], o[5 + i], __builtin_elementwise_fma(sv, o[9 + i], vv * o[13 + i]));
;           y0 = __builtin_elementwise_fma(St[i], o[16 + i], y0);
;           y1 = __builtin_elementwise_fma(St[i + 1], o[17 + i], y1);
;         }
;         yy[s4] = oct_sum((y0.x + y0.y) + (y1.x + y1.y));
;       }
;       if (cg == 0) {
; #pragma unroll
;         for (int s4 = 0; s4 < 4; ++s4) Yl[(sg + s4) * 32 + rp] = yy[s4];
	v_pk_fma_f32 v[58:59], v[198:199], v[50:51], v[58:59] op_sel_hi:[0,1,1]
	v_pk_fma_f32 v[72:73], v[198:199], v[52:53], v[72:73] op_sel_hi:[0,1,1]
	s_waitcnt lgkmcnt(6)
	v_pk_fma_f32 v[66:67], v[66:67], v[42:43], v[58:59]
	v_pk_fma_f32 v[64:65], v[64:65], v[44:45], v[72:73]
	v_pk_fma_f32 v[212:213], v[198:199], v[54:55], v[212:213] op_sel_hi:[0,1,1]
	v_pk_fma_f32 v[250:251], v[198:199], v[56:57], v[250:251] op_sel_hi:[0,1,1]
	v_pk_fma_f32 v[62:63], v[62:63], v[46:47], v[212:213]
	v_pk_fma_f32 v[60:61], v[60:61], v[48:49], v[250:251]
	ds_read_b128 v[50:53], v0 offset:21760
	ds_read_b128 v[54:57], v0 offset:21776
	ds_read_b128 v[42:45], v0 offset:5376
	ds_read_b128 v[46:49], v0 offset:5392
	s_waitcnt lgkmcnt(8)
	v_pk_fma_f32 v[58:59], v[66:67], v[154:155], 0 op_sel_hi:[1,1,0]
	v_pk_fma_f32 v[72:73], v[64:65], v[156:157], 0 op_sel_hi:[1,1,0]
	v_pk_fma_f32 v[58:59], v[62:63], v[246:247], v[58:59]
	v_pk_fma_f32 v[72:73], v[60:61], v[248:249], v[72:73]
	ds_read_b128 v[154:157], v0 offset:1280
	ds_read_b128 v[246:249], v0 offset:1296
	v_pk_add_f32 v[58:59], v[58:59], v[72:73]
	ds_read_b128 v[34:37], v0 offset:17920
	ds_read_b128 v[38:41], v0 offset:17936
	s_waitcnt lgkmcnt(10)
	v_pk_mul_f32 v[200:201], v[66:67], v[200:201]
	v_pk_mul_f32 v[202:203], v[64:65], v[202:203]
	v_pk_fma_f32 v[200:201], v[62:63], v[230:231], v[200:201]
	v_pk_fma_f32 v[202:203], v[60:61], v[232:233], v[202:203]
	v_pk_add_f32 v[200:201], v[200:201], v[202:203]
	v_add_f32_e32 v207, v58, v59
	v_add_f32_e32 v198, v200, v201
	s_waitcnt lgkmcnt(8)
	v_mov_b32_e32 v232, v159
	v_pk_mul_f32 v[58:59], v[68:69], v[232:233] op_sel_hi:[1,0]
	v_pk_mul_f32 v[72:73], v[70:71], v[232:233] op_sel_hi:[1,0]
	ds_read_b128 v[68:71], v0 offset:9728
	v_add_f32_dpp v198, v198, v198 quad_perm:[1,0,3,2] row_mask:0xf bank_mask:0xf bound_ctrl:1
	v_add_f32_dpp v207, v207, v207 quad_perm:[1,0,3,2] row_mask:0xf bank_mask:0xf bound_ctrl:1
	v_pk_mul_f32 v[212:213], v[150:151], v[232:233] op_sel_hi:[1,0]
	v_add_f32_dpp v198, v198, v198 quad_perm:[2,3,0,1] row_mask:0xf bank_mask:0xf bound_ctrl:1
	v_add_f32_dpp v207, v207, v207 quad_perm:[2,3,0,1] row_mask:0xf bank_mask:0xf bound_ctrl:1
	v_pk_mul_f32 v[250:251], v[152:153], v[232:233] op_sel_hi:[1,0]
	ds_read_b128 v[150:153], v0 offset:9744
	v_add_f32_dpp v198, v198, v198 row_half_mirror row_mask:0xf bank_mask:0xf bound_ctrl:1
	v_add_f32_dpp v163, v207, v207 row_half_mirror row_mask:0xf bank_mask:0xf bound_ctrl:1
	ds_read2st64_b32 v[158:159], v161 offset0:6 offset1:7
	ds_write_b32 v162, v163 offset:512
	s_waitcnt lgkmcnt(9)
	v_pk_fma_f32 v[58:59], v[198:199], v[50:51], v[58:59] op_sel_hi:[0,1,1]
	v_pk_fma_f32 v[72:73], v[198:199], v[52:53], v[72:73] op_sel_hi:[0,1,1]
	s_waitcnt lgkmcnt(7)
	v_pk_fma_f32 v[66:67], v[66:67], v[42:43], v[58:59]
	v_pk_fma_f32 v[64:65], v[64:65], v[44:45], v[72:73]
	v_pk_fma_f32 v[212:213], v[198:199], v[54:55], v[212:213] op_sel_hi:[0,1,1]
	v_pk_fma_f32 v[250:251], v[198:199], v[56:57], v[250:251] op_sel_hi:[0,1,1]
	v_pk_fma_f32 v[62:63], v[62:63], v[46:47], v[212:213]
	v_pk_fma_f32 v[60:61], v[60:61], v[48:49], v[250:251]
	ds_read_b128 v[50:53], v0 offset:22016
	ds_read_b128 v[54:57], v0 offset:22032
	ds_read_b128 v[42:45], v0 offset:5632
	ds_read_b128 v[46:49], v0 offset:5648
	s_waitcnt lgkmcnt(9)
	v_pk_fma_f32 v[58:59], v[66:67], v[154:155], 0 op_sel_hi:[1,1,0]
	v_pk_fma_f32 v[72:73], v[64:65], v[156:157], 0 op_sel_hi:[1,1,0]
	v_pk_fma_f32 v[58:59], v[62:63], v[246:247], v[58:59]
	v_pk_fma_f32 v[72:73], v[60:61], v[248:249], v[72:73]
	ds_read_b128 v[154:157], v0 offset:1536
	ds_read_b128 v[246:249], v0 offset:1552
	v_pk_add_f32 v[58:59], v[58:59], v[72:73]
	ds_read_b128 v[200:203], v0 offset:18176
	ds_read_b128 v[230:233], v0 offset:18192
	s_waitcnt lgkmcnt(11)
	v_pk_mul_f32 v[34:35], v[66:67], v[34:35]
	v_pk_mul_f32 v[36:37], v[64:65], v[36:37]
	v_pk_fma_f32 v[34:35], v[62:63], v[38:39], v[34:35]
	v_pk_fma_f32 v[36:37], v[60:61], v[40:41], v[36:37]
	v_pk_add_f32 v[34:35], v[34:35], v[36:37]
	v_add_f32_e32 v207, v58, v59
	v_add_f32_e32 v198, v34, v35
	s_waitcnt lgkmcnt(8)
	v_pk_mul_f32 v[58:59], v[68:69], v[158:159] op_sel_hi:[1,0]
	v_pk_mul_f32 v[72:73], v[70:71], v[158:159] op_sel_hi:[1,0]
	ds_read_b128 v[68:71], v0 offset:9984
	v_add_f32_dpp v198, v198, v198 quad_perm:[1,0,3,2] row_mask:0xf bank_mask:0xf bound_ctrl:1
	v_add_f32_dpp v207, v207, v207 quad_perm:[1,0,3,2] row_mask:0xf bank_mask:0xf bound_ctrl:1
	v_pk_mul_f32 v[212:213], v[150:151], v[158:159] op_sel_hi:[1,0]
	v_add_f32_dpp v198, v198, v198 quad_perm:[2,3,0,1] row_mask:0xf bank_mask:0xf bound_ctrl:1
	v_add_f32_dpp v207, v207, v207 quad_perm:[2,3,0,1] row_mask:0xf bank_mask:0xf bound_ctrl:1
	v_pk_mul_f32 v[250:251], v[152:153], v[158:159] op_sel_hi:[1,0]
	ds_read_b128 v[150:153], v0 offset:10000
	v_add_f32_dpp v198, v198, v198 row_half_mirror row_mask:0xf bank_mask:0xf bound_ctrl:1
	v_add_f32_dpp v205, v207, v207 row_half_mirror row_mask:0xf bank_mask:0xf bound_ctrl:1
	ds_write_b32 v162, v205 offset:640
	s_waitcnt lgkmcnt(8)
	v_pk_fma_f32 v[58:59], v[198:199], v[50:51], v[58:59] op_sel_hi:[0,1,1]
	v_pk_fma_f32 v[72:73], v[198:199], v[52:53], v[72:73] op_sel_hi:[0,1,1]
	s_waitcnt lgkmcnt(6)
	v_pk_fma_f32 v[66:67], v[66:67], v[42:43], v[58:59]
	v_pk_fma_f32 v[64:65], v[64:65], v[44:45], v[72:73]
	v_pk_fma_f32 v[212:213], v[198:199], v[54:55], v[212:213] op_sel_hi:[0,1,1]
	v_pk_fma_f32 v[250:251], v[198:199], v[56:57], v[250:251] op_sel_hi:[0,1,1]
	v_pk_fma_f32 v[62:63], v[62:63], v[46:47], v[212:213]
	v_pk_fma_f32 v[60:61], v[60:61], v[48:49], v[250:251]
	ds_read_b128 v[50:53], v0 offset:22272
	ds_read_b128 v[54:57], v0 offset:22288
	ds_read_b128 v[42:45], v0 offset:5888
	ds_read_b128 v[46:49], v0 offset:5904
	s_waitcnt lgkmcnt(8)
; DI float oct_sum(float v) { v += dpp_f<0xB1>(v); v += dpp_f<0x4E>(v); v += dpp_f<0x141>(v); return v; }
; DI void scan_item(const Params& p, int b, int h, int half, char* smem, unsigned* pgen, unsigned kp) {
;     ...
;       for (int s4 = 0; s4 < 4; ++s4) {
;         const int s = sg + s4;
;         const f32x2* a2 = (const f32x2*)(Al + s * 64 + cg * 8);
;         const f32x2* w2 = (const f32x2*)(Wl + s * 64 + cg * 8);
;         const f32x2* b2 = (const f32x2*)(Bl + s * 64 + cg * 8);
;         const f32x2* k2 = (const f32x2*)(Kl + s * 64 + cg * 8);
;         const f32x2* r2 = (const f32x2*)(Rl + s * 64 + cg * 8);
;         f32x2 o[20];
; #pragma unroll
;         for (int i = 0; i < 4; ++i) { o[i] = a2[i]; o[4 + i] = w2[i]; o[8 + i] = b2[i]; o[12 + i] = k2[i]; o[16 + i] = r2[i]; }
;         const float vr = Vl[s * 64 + 32 * half + rp];
;         f32x2 p0 = St[0] * o[0], p1 = St[1] * o[1];
;         p0 = __builtin_elementwise_fma(St[2], o[2], p0); p1 = __builtin_elementwise_fma(St[3], o[3], p1);
;         const float sa = oct_sum((p0.x + p0.y) + (p1.x + p1.y));
;         const f32x2 sv = {sa, sa}, vv = {vr, vr};
;         f32x2 y0 = {0.f, 0.f}, y1 = {0.f, 0.f};
; #pragma unroll
;         for (int i = 0; i < 4; i += 2) {
;           St[i] = __builtin_elementwise_fma(St[i], o[4 + i], __builtin_elementwise_fma(sv, o[8 + i], vv * o[12 + i]));
;           St[i + 1] = __builtin_elementwise_fma(St[i + 1], o[5 + i], __builtin_elementwise_fma(sv, o[9 + i], vv * o[13 + i]));
;           y0 = __builtin_elementwise_fma(St[i], o[16 + i], y0);
;           y1 = __builtin_elementwise_fma(St[i + 1], o[17 + i], y1);
;         }
;         yy[s4] = oct_sum((y0.x + y0.y) + (y1.x + y1.y));
;       }
;       if (cg == 0) {
; #pragma unroll
;         for (int s4 = 0; s4 < 4; ++s4) Yl[(sg + s4) * 32 + rp] = yy[s4];
	v_pk_fma_f32 v[58:59], v[66:67], v[154:155], 0 op_sel_hi:[1,1,0]
	v_pk_fma_f32 v[72:73], v[64:65], v[156:157], 0 op_sel_hi:[1,1,0]
	v_pk_fma_f32 v[58:59], v[62:63], v[246:247], v[58:59]
	v_pk_fma_f32 v[72:73], v[60:61], v[248:249], v[72:73]
	ds_read_b128 v[154:157], v0 offset:1792
	ds_read_b128 v[246:249], v0 offset:1808
	v_pk_add_f32 v[58:59], v[58:59], v[72:73]
	ds_read_b128 v[34:37], v0 offset:18432
	ds_read_b128 v[38:41], v0 offset:18448
	s_waitcnt lgkmcnt(10)
	v_pk_mul_f32 v[200:201], v[66:67], v[200:201]
	v_pk_mul_f32 v[202:203], v[64:65], v[202:203]
	v_pk_fma_f32 v[200:201], v[62:63], v[230:231], v[200:201]
	v_pk_fma_f32 v[202:203], v[60:61], v[232:233], v[202:203]
	v_pk_add_f32 v[200:201], v[200:201], v[202:203]
	v_add_f32_e32 v207, v58, v59
	v_add_f32_e32 v198, v200, v201
	s_waitcnt lgkmcnt(8)
	v_mov_b32_e32 v232, v159
	v_pk_mul_f32 v[58:59], v[68:69], v[232:233] op_sel_hi:[1,0]
	v_pk_mul_f32 v[72:73], v[70:71], v[232:233] op_sel_hi:[1,0]
	ds_read_b128 v[68:71], v0 offset:10240
	v_add_f32_dpp v198, v198, v198 quad_perm:[1,0,3,2] row_mask:0xf bank_mask:0xf bound_ctrl:1
	v_add_f32_dpp v207, v207, v207 quad_perm:[1,0,3,2] row_mask:0xf bank_mask:0xf bound_ctrl:1
	v_pk_mul_f32 v[212:213], v[150:151], v[232:233] op_sel_hi:[1,0]
	v_add_f32_dpp v198, v198, v198 quad_perm:[2,3,0,1] row_mask:0xf bank_mask:0xf bound_ctrl:1
	v_add_f32_dpp v207, v207, v207 quad_perm:[2,3,0,1] row_mask:0xf bank_mask:0xf bound_ctrl:1
	v_pk_mul_f32 v[250:251], v[152:153], v[232:233] op_sel_hi:[1,0]
	ds_read_b128 v[150:153], v0 offset:10256
	v_add_f32_dpp v198, v198, v198 row_half_mirror row_mask:0xf bank_mask:0xf bound_ctrl:1
	v_add_f32_dpp v163, v207, v207 row_half_mirror row_mask:0xf bank_mask:0xf bound_ctrl:1
	ds_read2st64_b32 v[158:159], v161 offset0:8 offset1:9
	ds_write_b32 v162, v163 offset:768
	s_waitcnt lgkmcnt(9)
	v_pk_fma_f32 v[58:59], v[198:199], v[50:51], v[58:59] op_sel_hi:[0,1,1]
	v_pk_fma_f32 v[72:73], v[198:199], v[52:53], v[72:73] op_sel_hi:[0,1,1]
	s_waitcnt lgkmcnt(7)
	v_pk_fma_f32 v[66:67], v[66:67], v[42:43], v[58:59]
	v_pk_fma_f32 v[64:65], v[64:65], v[44:45], v[72:73]
	v_pk_fma_f32 v[212:213], v[198:199], v[54:55], v[212:213] op_sel_hi:[0,1,1]
	v_pk_fma_f32 v[250:251], v[198:199], v[56:57], v[250:251] op_sel_hi:[0,1,1]
	v_pk_fma_f32 v[62:63], v[62:63], v[46:47], v[212:213]
	v_pk_fma_f32 v[60:61], v[60:61], v[48:49], v[250:251]
	ds_read_b128 v[50:53], v0 offset:22528
	ds_read_b128 v[54:57], v0 offset:22544
	ds_read_b128 v[42:45], v0 offset:6144
	ds_read_b128 v[46:49], v0 offset:6160
	s_waitcnt lgkmcnt(9)
	v_pk_fma_f32 v[58:59], v[66:67], v[154:155], 0 op_sel_hi:[1,1,0]
	v_pk_fma_f32 v[72:73], v[64:65], v[156:157], 0 op_sel_hi:[1,1,0]
	v_pk_fma_f32 v[58:59], v[62:63], v[246:247], v[58:59]
	v_pk_fma_f32 v[72:73], v[60:61], v[248:249], v[72:73]
	ds_read_b128 v[154:157], v0 offset:2048
	ds_read_b128 v[246:249], v0 offset:2064
	v_pk_add_f32 v[58:59], v[58:59], v[72:73]
	ds_read_b128 v[200:203], v0 offset:18688
	ds_read_b128 v[230:233], v0 offset:18704
	s_waitcnt lgkmcnt(11)
	v_pk_mul_f32 v[34:35], v[66:67], v[34:35]
	v_pk_mul_f32 v[36:37], v[64:65], v[36:37]
	v_pk_fma_f32 v[34:35], v[62:63], v[38:39], v[34:35]
	v_pk_fma_f32 v[36:37], v[60:61], v[40:41], v[36:37]
	v_pk_add_f32 v[34:35], v[34:35], v[36:37]
	v_add_f32_e32 v207, v58, v59
	v_add_f32_e32 v198, v34, v35
	s_waitcnt lgkmcnt(8)
	v_pk_mul_f32 v[58:59], v[68:69], v[158:159] op_sel_hi:[1,0]
	v_pk_mul_f32 v[72:73], v[70:71], v[158:159] op_sel_hi:[1,0]
	ds_read_b128 v[68:71], v0 offset:10496
	v_add_f32_dpp v198, v198, v198 quad_perm:[1,0,3,2] row_mask:0xf bank_mask:0xf bound_ctrl:1
	v_add_f32_dpp v207, v207, v207 quad_perm:[1,0,3,2] row_mask:0xf bank_mask:0xf bound_ctrl:1
	v_pk_mul_f32 v[212:213], v[150:151], v[158:159] op_sel_hi:[1,0]
	v_add_f32_dpp v198, v198, v198 quad_perm:[2,3,0,1] row_mask:0xf bank_mask:0xf bound_ctrl:1
	v_add_f32_dpp v207, v207, v207 quad_perm:[2,3,0,1] row_mask:0xf bank_mask:0xf bound_ctrl:1
	v_pk_mul_f32 v[250:251], v[152:153], v[158:159] op_sel_hi:[1,0]
	ds_read_b128 v[150:153], v0 offset:10512
	v_add_f32_dpp v198, v198, v198 row_half_mirror row_mask:0xf bank_mask:0xf bound_ctrl:1
	v_add_f32_dpp v205, v207, v207 row_half_mirror row_mask:0xf bank_mask:0xf bound_ctrl:1
	ds_write_b32 v162, v205 offset:896
	s_waitcnt lgkmcnt(8)
	v_pk_fma_f32 v[58:59], v[198:199], v[50:51], v[58:59] op_sel_hi:[0,1,1]
	v_pk_fma_f32 v[72:73], v[198:199], v[52:53], v[72:73] op_sel_hi:[0,1,1]
	s_waitcnt lgkmcnt(6)
	v_pk_fma_f32 v[66:67], v[66:67], v[42:43], v[58:59]
	v_pk_fma_f32 v[64:65], v[64:65], v[44:45], v[72:73]
	v_pk_fma_f32 v[212:213], v[198:199], v[54:55], v[212:213] op_sel_hi:[0,1,1]
	v_pk_fma_f32 v[250:251], v[198:199], v[56:57], v[250:251] op_sel_hi:[0,1,1]
	v_pk_fma_f32 v[62:63], v[62:63], v[46:47], v[212:213]
	v_pk_fma_f32 v[60:61], v[60:61], v[48:49], v[250:251]
	ds_read_b128 v[50:53], v0 offset:22784
	ds_read_b128 v[54:57], v0 offset:22800
	ds_read_b128 v[42:45], v0 offset:6400
	ds_read_b128 v[46:49], v0 offset:6416
	s_waitcnt lgkmcnt(8)
	v_pk_fma_f32 v[58:59], v[66:67], v[154:155], 0 op_sel_hi:[1,1,0]
	v_pk_fma_f32 v[72:73], v[64:65], v[156:157], 0 op_sel_hi:[1,1,0]
	v_pk_fma_f32 v[58:59], v[62:63], v[246:247], v[58:59]
	v_pk_fma_f32 v[72:73], v[60:61], v[248:249], v[72:73]
	ds_read_b128 v[154:157], v0 offset:2304
	ds_read_b128 v[246:249], v0 offset:2320
	v_pk_add_f32 v[58:59], v[58:59], v[72:73]
	ds_read_b128 v[34:37], v0 offset:18944
	ds_read_b128 v[38:41], v0 offset:18960
	s_waitcnt lgkmcnt(10)
	v_pk_mul_f32 v[200:201], v[66:67], v[200:201]
	v_pk_mul_f32 v[202:203], v[64:65], v[202:203]
	v_pk_fma_f32 v[200:201], v[62:63], v[230:231], v[200:201]
	v_pk_fma_f32 v[202:203], v[60:61], v[232:233], v[202:203]
	v_pk_add_f32 v[200:201], v[200:201], v[202:203]
	v_add_f32_e32 v207, v58, v59
	v_add_f32_e32 v198, v200, v201
	s_waitcnt lgkmcnt(8)
; DI float oct_sum(float v) { v += dpp_f<0xB1>(v); v += dpp_f<0x4E>(v); v += dpp_f<0x141>(v); return v; }
; DI void scan_item(const Params& p, int b, int h, int half, char* smem, unsigned* pgen, unsigned kp) {
;     ...
;       for (int s4 = 0; s4 < 4; ++s4) {
;         const int s = sg + s4;
;         const f32x2* a2 = (const f32x2*)(Al + s * 64 + cg * 8);
;         const f32x2* w2 = (const f32x2*)(Wl + s * 64 + cg * 8);
;         const f32x2* b2 = (const f32x2*)(Bl + s * 64 + cg * 8);
;         const f32x2* k2 = (const f32x2*)(Kl + s * 64 + cg * 8);
;         const f32x2* r2 = (const f32x2*)(Rl + s * 64 + cg * 8);
;         f32x2 o[20];
; #pragma unroll
;         for (int i = 0; i < 4; ++i) { o[i] = a2[i]; o[4 + i] = w2[i]; o[8 + i] = b2[i]; o[12 + i] = k2[i]; o[16 + i] = r2[i]; }
;         const float vr = Vl[s * 64 + 32 * half + rp];
;         f32x2 p0 = St[0] * o[0], p1 = St[1] * o[1];
;         p0 = __builtin_elementwise_fma(St[2], o[2], p0); p1 = __builtin_elementwise_fma(St[3], o[3], p1);
;         const float sa = oct_sum((p0.x + p0.y) + (p1.x + p1.y));
;         const f32x2 sv = {sa, sa}, vv = {vr, vr};
;         f32x2 y0 = {0.f, 0.f}, y1 = {0.f, 0.f};
; #pragma unroll
;         for (int i = 0; i < 4; i += 2) {
;           St[i] = __builtin_elementwise_fma(St[i], o[4 + i], __builtin_elementwise_fma(sv, o[8 + i], vv * o[12 + i]));
;           St[i + 1] = __builtin_elementwise_fma(St[i + 1], o[5 + i], __builtin_elementwise_fma(sv, o[9 + i], vv * o[13 + i]));
;           y0 = __builtin_elementwise_fma(St[i], o[16 + i], y0);
;           y1 = __builtin_elementwise_fma(St[i + 1], o[17 + i], y1);
;         }
;         yy[s4] = oct_sum((y0.x + y0.y) + (y1.x + y1.y));
;       }
;       if (cg == 0) {
; #pragma unroll
;         for (int s4 = 0; s4 < 4; ++s4) Yl[(sg + s4) * 32 + rp] = yy[s4];
	v_mov_b32_e32 v232, v159
	v_pk_mul_f32 v[58:59], v[68:69], v[232:233] op_sel_hi:[1,0]
	v_pk_mul_f32 v[72:73], v[70:71], v[232:233] op_sel_hi:[1,0]
	ds_read_b128 v[68:71], v0 offset:10752
	v_add_f32_dpp v198, v198, v198 quad_perm:[1,0,3,2] row_mask:0xf bank_mask:0xf bound_ctrl:1
	v_add_f32_dpp v207, v207, v207 quad_perm:[1,0,3,2] row_mask:0xf bank_mask:0xf bound_ctrl:1
	v_pk_mul_f32 v[212:213], v[150:151], v[232:233] op_sel_hi:[1,0]
	v_add_f32_dpp v198, v198, v198 quad_perm:[2,3,0,1] row_mask:0xf bank_mask:0xf bound_ctrl:1
	v_add_f32_dpp v207, v207, v207 quad_perm:[2,3,0,1] row_mask:0xf bank_mask:0xf bound_ctrl:1
	v_pk_mul_f32 v[250:251], v[152:153], v[232:233] op_sel_hi:[1,0]
	ds_read_b128 v[150:153], v0 offset:10768
	v_add_f32_dpp v198, v198, v198 row_half_mirror row_mask:0xf bank_mask:0xf bound_ctrl:1
	v_add_f32_dpp v163, v207, v207 row_half_mirror row_mask:0xf bank_mask:0xf bound_ctrl:1
	ds_read2st64_b32 v[158:159], v161 offset0:10 offset1:11
	ds_write_b32 v162, v163 offset:1024
	s_waitcnt lgkmcnt(9)
	v_pk_fma_f32 v[58:59], v[198:199], v[50:51], v[58:59] op_sel_hi:[0,1,1]
	v_pk_fma_f32 v[72:73], v[198:199], v[52:53], v[72:73] op_sel_hi:[0,1,1]
	s_waitcnt lgkmcnt(7)
	v_pk_fma_f32 v[66:67], v[66:67], v[42:43], v[58:59]
	v_pk_fma_f32 v[64:65], v[64:65], v[44:45], v[72:73]
	v_pk_fma_f32 v[212:213], v[198:199], v[54:55], v[212:213] op_sel_hi:[0,1,1]
	v_pk_fma_f32 v[250:251], v[198:199], v[56:57], v[250:251] op_sel_hi:[0,1,1]
	v_pk_fma_f32 v[62:63], v[62:63], v[46:47], v[212:213]
	v_pk_fma_f32 v[60:61], v[60:61], v[48:49], v[250:251]
	ds_read_b128 v[50:53], v0 offset:23040
	ds_read_b128 v[54:57], v0 offset:23056
	ds_read_b128 v[42:45], v0 offset:6656
	ds_read_b128 v[46:49], v0 offset:6672
	s_waitcnt lgkmcnt(9)
	v_pk_fma_f32 v[58:59], v[66:67], v[154:155], 0 op_sel_hi:[1,1,0]
	v_pk_fma_f32 v[72:73], v[64:65], v[156:157], 0 op_sel_hi:[1,1,0]
	v_pk_fma_f32 v[58:59], v[62:63], v[246:247], v[58:59]
	v_pk_fma_f32 v[72:73], v[60:61], v[248:249], v[72:73]
	ds_read_b128 v[154:157], v0 offset:2560
	ds_read_b128 v[246:249], v0 offset:2576
	v_pk_add_f32 v[58:59], v[58:59], v[72:73]
	ds_read_b128 v[200:203], v0 offset:19200
	ds_read_b128 v[230:233], v0 offset:19216
	s_waitcnt lgkmcnt(11)
	v_pk_mul_f32 v[34:35], v[66:67], v[34:35]
	v_pk_mul_f32 v[36:37], v[64:65], v[36:37]
	v_pk_fma_f32 v[34:35], v[62:63], v[38:39], v[34:35]
	v_pk_fma_f32 v[36:37], v[60:61], v[40:41], v[36:37]
	v_pk_add_f32 v[34:35], v[34:35], v[36:37]
	v_add_f32_e32 v207, v58, v59
	v_add_f32_e32 v198, v34, v35
	s_waitcnt lgkmcnt(8)
	v_pk_mul_f32 v[58:59], v[68:69], v[158:159] op_sel_hi:[1,0]
	v_pk_mul_f32 v[72:73], v[70:71], v[158:159] op_sel_hi:[1,0]
	ds_read_b128 v[68:71], v0 offset:11008
	v_add_f32_dpp v198, v198, v198 quad_perm:[1,0,3,2] row_mask:0xf bank_mask:0xf bound_ctrl:1
	v_add_f32_dpp v207, v207, v207 quad_perm:[1,0,3,2] row_mask:0xf bank_mask:0xf bound_ctrl:1
	v_pk_mul_f32 v[212:213], v[150:151], v[158:159] op_sel_hi:[1,0]
	v_add_f32_dpp v198, v198, v198 quad_perm:[2,3,0,1] row_mask:0xf bank_mask:0xf bound_ctrl:1
	v_add_f32_dpp v207, v207, v207 quad_perm:[2,3,0,1] row_mask:0xf bank_mask:0xf bound_ctrl:1
	v_pk_mul_f32 v[250:251], v[152:153], v[158:159] op_sel_hi:[1,0]
	ds_read_b128 v[150:153], v0 offset:11024
	v_add_f32_dpp v198, v198, v198 row_half_mirror row_mask:0xf bank_mask:0xf bound_ctrl:1
	v_add_f32_dpp v205, v207, v207 row_half_mirror row_mask:0xf bank_mask:0xf bound_ctrl:1
	ds_write_b32 v162, v205 offset:1152
	s_waitcnt lgkmcnt(8)
	v_pk_fma_f32 v[58:59], v[198:199], v[50:51], v[58:59] op_sel_hi:[0,1,1]
	v_pk_fma_f32 v[72:73], v[198:199], v[52:53], v[72:73] op_sel_hi:[0,1,1]
	s_waitcnt lgkmcnt(6)
	v_pk_fma_f32 v[66:67], v[66:67], v[42:43], v[58:59]
	v_pk_fma_f32 v[64:65], v[64:65], v[44:45], v[72:73]
	v_pk_fma_f32 v[212:213], v[198:199], v[54:55], v[212:213] op_sel_hi:[0,1,1]
	v_pk_fma_f32 v[250:251], v[198:199], v[56:57], v[250:251] op_sel_hi:[0,1,1]
	v_pk_fma_f32 v[62:63], v[62:63], v[46:47], v[212:213]
	v_pk_fma_f32 v[60:61], v[60:61], v[48:49], v[250:251]
	ds_read_b128 v[50:53], v0 offset:23296
	ds_read_b128 v[54:57], v0 offset:23312
	ds_read_b128 v[42:45], v0 offset:6912
	ds_read_b128 v[46:49], v0 offset:6928
	s_waitcnt lgkmcnt(8)
	v_pk_fma_f32 v[58:59], v[66:67], v[154:155], 0 op_sel_hi:[1,1,0]
	v_pk_fma_f32 v[72:73], v[64:65], v[156:157], 0 op_sel_hi:[1,1,0]
	v_pk_fma_f32 v[58:59], v[62:63], v[246:247], v[58:59]
	v_pk_fma_f32 v[72:73], v[60:61], v[248:249], v[72:73]
	ds_read_b128 v[154:157], v0 offset:2816
	ds_read_b128 v[246:249], v0 offset:2832
	v_pk_add_f32 v[58:59], v[58:59], v[72:73]
	ds_read_b128 v[34:37], v0 offset:19456
	ds_read_b128 v[38:41], v0 offset:19472
	s_waitcnt lgkmcnt(10)
	v_pk_mul_f32 v[200:201], v[66:67], v[200:201]
	v_pk_mul_f32 v[202:203], v[64:65], v[202:203]
	v_pk_fma_f32 v[200:201], v[62:63], v[230:231], v[200:201]
	v_pk_fma_f32 v[202:203], v[60:61], v[232:233], v[202:203]
	v_pk_add_f32 v[200:201], v[200:201], v[202:203]
	v_add_f32_e32 v207, v58, v59
	v_add_f32_e32 v198, v200, v201
	s_waitcnt lgkmcnt(8)
	v_mov_b32_e32 v232, v159
	v_pk_mul_f32 v[58:59], v[68:69], v[232:233] op_sel_hi:[1,0]
	v_pk_mul_f32 v[72:73], v[70:71], v[232:233] op_sel_hi:[1,0]
	ds_read_b128 v[68:71], v0 offset:11264
	v_add_f32_dpp v198, v198, v198 quad_perm:[1,0,3,2] row_mask:0xf bank_mask:0xf bound_ctrl:1
	v_add_f32_dpp v207, v207, v207 quad_perm:[1,0,3,2] row_mask:0xf bank_mask:0xf bound_ctrl:1
	v_pk_mul_f32 v[212:213], v[150:151], v[232:233] op_sel_hi:[1,0]
	v_add_f32_dpp v198, v198, v198 quad_perm:[2,3,0,1] row_mask:0xf bank_mask:0xf bound_ctrl:1
	v_add_f32_dpp v207, v207, v207 quad_perm:[2,3,0,1] row_mask:0xf bank_mask:0xf bound_ctrl:1
	v_pk_mul_f32 v[250:251], v[152:153], v[232:233] op_sel_hi:[1,0]
	ds_read_b128 v[150:153], v0 offset:11280
	v_add_f32_dpp v198, v198, v198 row_half_mirror row_mask:0xf bank_mask:0xf bound_ctrl:1
	v_add_f32_dpp v163, v207, v207 row_half_mirror row_mask:0xf bank_mask:0xf bound_ctrl:1
	ds_read2st64_b32 v[158:159], v161 offset0:12 offset1:13
	ds_write_b32 v162, v163 offset:1280
	s_waitcnt lgkmcnt(9)
; DI float oct_sum(float v) { v += dpp_f<0xB1>(v); v += dpp_f<0x4E>(v); v += dpp_f<0x141>(v); return v; }
; DI void scan_item(const Params& p, int b, int h, int half, char* smem, unsigned* pgen, unsigned kp) {
;     ...
;       for (int s4 = 0; s4 < 4; ++s4) {
;         const int s = sg + s4;
;         const f32x2* a2 = (const f32x2*)(Al + s * 64 + cg * 8);
;         const f32x2* w2 = (const f32x2*)(Wl + s * 64 + cg * 8);
;         const f32x2* b2 = (const f32x2*)(Bl + s * 64 + cg * 8);
;         const f32x2* k2 = (const f32x2*)(Kl + s * 64 + cg * 8);
;         const f32x2* r2 = (const f32x2*)(Rl + s * 64 + cg * 8);
;         f32x2 o[20];
; #pragma unroll
;         for (int i = 0; i < 4; ++i) { o[i] = a2[i]; o[4 + i] = w2[i]; o[8 + i] = b2[i]; o[12 + i] = k2[i]; o[16 + i] = r2[i]; }
;         const float vr = Vl[s * 64 + 32 * half + rp];
;         f32x2 p0 = St[0] * o[0], p1 = St[1] * o[1];
;         p0 = __builtin_elementwise_fma(St[2], o[2], p0); p1 = __builtin_elementwise_fma(St[3], o[3], p1);
;         const float sa = oct_sum((p0.x + p0.y) + (p1.x + p1.y));
;         const f32x2 sv = {sa, sa}, vv = {vr, vr};
;         f32x2 y0 = {0.f, 0.f}, y1 = {0.f, 0.f};
; #pragma unroll
;         for (int i = 0; i < 4; i += 2) {
;           St[i] = __builtin_elementwise_fma(St[i], o[4 + i], __builtin_elementwise_fma(sv, o[8 + i], vv * o[12 + i]));
;           St[i + 1] = __builtin_elementwise_fma(St[i + 1], o[5 + i], __builtin_elementwise_fma(sv, o[9 + i], vv * o[13 + i]));
;           y0 = __builtin_elementwise_fma(St[i], o[16 + i], y0);
;           y1 = __builtin_elementwise_fma(St[i + 1], o[17 + i], y1);
;         }
;         yy[s4] = oct_sum((y0.x + y0.y) + (y1.x + y1.y));
;       }
;       if (cg == 0) {
; #pragma unroll
;         for (int s4 = 0; s4 < 4; ++s4) Yl[(sg + s4) * 32 + rp] = yy[s4];
	v_pk_fma_f32 v[58:59], v[198:199], v[50:51], v[58:59] op_sel_hi:[0,1,1]
	v_pk_fma_f32 v[72:73], v[198:199], v[52:53], v[72:73] op_sel_hi:[0,1,1]
	s_waitcnt lgkmcnt(7)
	v_pk_fma_f32 v[66:67], v[66:67], v[42:43], v[58:59]
	v_pk_fma_f32 v[64:65], v[64:65], v[44:45], v[72:73]
	v_pk_fma_f32 v[212:213], v[198:199], v[54:55], v[212:213] op_sel_hi:[0,1,1]
	v_pk_fma_f32 v[250:251], v[198:199], v[56:57], v[250:251] op_sel_hi:[0,1,1]
	v_pk_fma_f32 v[62:63], v[62:63], v[46:47], v[212:213]
	v_pk_fma_f32 v[60:61], v[60:61], v[48:49], v[250:251]
	ds_read_b128 v[50:53], v0 offset:23552
	ds_read_b128 v[54:57], v0 offset:23568
	ds_read_b128 v[42:45], v0 offset:7168
	ds_read_b128 v[46:49], v0 offset:7184
	s_waitcnt lgkmcnt(9)
	v_pk_fma_f32 v[58:59], v[66:67], v[154:155], 0 op_sel_hi:[1,1,0]
	v_pk_fma_f32 v[72:73], v[64:65], v[156:157], 0 op_sel_hi:[1,1,0]
	v_pk_fma_f32 v[58:59], v[62:63], v[246:247], v[58:59]
	v_pk_fma_f32 v[72:73], v[60:61], v[248:249], v[72:73]
	ds_read_b128 v[154:157], v0 offset:3072
	ds_read_b128 v[246:249], v0 offset:3088
	v_pk_add_f32 v[58:59], v[58:59], v[72:73]
	ds_read_b128 v[200:203], v0 offset:19712
	ds_read_b128 v[230:233], v0 offset:19728
	s_waitcnt lgkmcnt(11)
	v_pk_mul_f32 v[34:35], v[66:67], v[34:35]
	v_pk_mul_f32 v[36:37], v[64:65], v[36:37]
	v_pk_fma_f32 v[34:35], v[62:63], v[38:39], v[34:35]
	v_pk_fma_f32 v[36:37], v[60:61], v[40:41], v[36:37]
	v_pk_add_f32 v[34:35], v[34:35], v[36:37]
	v_add_f32_e32 v207, v58, v59
	v_add_f32_e32 v198, v34, v35
	s_waitcnt lgkmcnt(8)
	v_pk_mul_f32 v[58:59], v[68:69], v[158:159] op_sel_hi:[1,0]
	v_pk_mul_f32 v[72:73], v[70:71], v[158:159] op_sel_hi:[1,0]
	ds_read_b128 v[68:71], v0 offset:11520
	v_add_f32_dpp v198, v198, v198 quad_perm:[1,0,3,2] row_mask:0xf bank_mask:0xf bound_ctrl:1
	v_add_f32_dpp v207, v207, v207 quad_perm:[1,0,3,2] row_mask:0xf bank_mask:0xf bound_ctrl:1
	v_pk_mul_f32 v[212:213], v[150:151], v[158:159] op_sel_hi:[1,0]
	v_add_f32_dpp v198, v198, v198 quad_perm:[2,3,0,1] row_mask:0xf bank_mask:0xf bound_ctrl:1
	v_add_f32_dpp v207, v207, v207 quad_perm:[2,3,0,1] row_mask:0xf bank_mask:0xf bound_ctrl:1
	v_pk_mul_f32 v[250:251], v[152:153], v[158:159] op_sel_hi:[1,0]
	ds_read_b128 v[150:153], v0 offset:11536
	v_add_f32_dpp v198, v198, v198 row_half_mirror row_mask:0xf bank_mask:0xf bound_ctrl:1
	v_add_f32_dpp v205, v207, v207 row_half_mirror row_mask:0xf bank_mask:0xf bound_ctrl:1
	ds_write_b32 v162, v205 offset:1408
	s_waitcnt lgkmcnt(8)
	v_pk_fma_f32 v[58:59], v[198:199], v[50:51], v[58:59] op_sel_hi:[0,1,1]
	v_pk_fma_f32 v[72:73], v[198:199], v[52:53], v[72:73] op_sel_hi:[0,1,1]
	s_waitcnt lgkmcnt(6)
	v_pk_fma_f32 v[66:67], v[66:67], v[42:43], v[58:59]
	v_pk_fma_f32 v[64:65], v[64:65], v[44:45], v[72:73]
	v_pk_fma_f32 v[212:213], v[198:199], v[54:55], v[212:213] op_sel_hi:[0,1,1]
	v_pk_fma_f32 v[250:251], v[198:199], v[56:57], v[250:251] op_sel_hi:[0,1,1]
	v_pk_fma_f32 v[62:63], v[62:63], v[46:47], v[212:213]
	v_pk_fma_f32 v[60:61], v[60:61], v[48:49], v[250:251]
	ds_read_b128 v[50:53], v0 offset:23808
	ds_read_b128 v[54:57], v0 offset:23824
	ds_read_b128 v[42:45], v0 offset:7424
	ds_read_b128 v[46:49], v0 offset:7440
	s_waitcnt lgkmcnt(8)
	v_pk_fma_f32 v[58:59], v[66:67], v[154:155], 0 op_sel_hi:[1,1,0]
	v_pk_fma_f32 v[72:73], v[64:65], v[156:157], 0 op_sel_hi:[1,1,0]
	v_pk_fma_f32 v[58:59], v[62:63], v[246:247], v[58:59]
	v_pk_fma_f32 v[72:73], v[60:61], v[248:249], v[72:73]
	ds_read_b128 v[154:157], v0 offset:3328
	ds_read_b128 v[246:249], v0 offset:3344
	v_pk_add_f32 v[58:59], v[58:59], v[72:73]
	ds_read_b128 v[34:37], v0 offset:19968
	ds_read_b128 v[38:41], v0 offset:19984
	s_waitcnt lgkmcnt(10)
	v_pk_mul_f32 v[200:201], v[66:67], v[200:201]
	v_pk_mul_f32 v[202:203], v[64:65], v[202:203]
	v_pk_fma_f32 v[200:201], v[62:63], v[230:231], v[200:201]
	v_pk_fma_f32 v[202:203], v[60:61], v[232:233], v[202:203]
	v_pk_add_f32 v[200:201], v[200:201], v[202:203]
	v_add_f32_e32 v207, v58, v59
	v_add_f32_e32 v198, v200, v201
	s_waitcnt lgkmcnt(8)
	v_mov_b32_e32 v232, v159
	v_pk_mul_f32 v[58:59], v[68:69], v[232:233] op_sel_hi:[1,0]
	v_pk_mul_f32 v[72:73], v[70:71], v[232:233] op_sel_hi:[1,0]
	ds_read_b128 v[68:71], v0 offset:11776
	v_add_f32_dpp v198, v198, v198 quad_perm:[1,0,3,2] row_mask:0xf bank_mask:0xf bound_ctrl:1
	v_add_f32_dpp v207, v207, v207 quad_perm:[1,0,3,2] row_mask:0xf bank_mask:0xf bound_ctrl:1
	v_pk_mul_f32 v[212:213], v[150:151], v[232:233] op_sel_hi:[1,0]
	v_add_f32_dpp v198, v198, v198 quad_perm:[2,3,0,1] row_mask:0xf bank_mask:0xf bound_ctrl:1
	v_add_f32_dpp v207, v207, v207 quad_perm:[2,3,0,1] row_mask:0xf bank_mask:0xf bound_ctrl:1
	v_pk_mul_f32 v[250:251], v[152:153], v[232:233] op_sel_hi:[1,0]
	ds_read_b128 v[150:153], v0 offset:11792
	v_add_f32_dpp v198, v198, v198 row_half_mirror row_mask:0xf bank_mask:0xf bound_ctrl:1
	v_add_f32_dpp v163, v207, v207 row_half_mirror row_mask:0xf bank_mask:0xf bound_ctrl:1
	ds_read2st64_b32 v[158:159], v161 offset0:14 offset1:15
	ds_write_b32 v162, v163 offset:1536
	s_waitcnt lgkmcnt(9)
	v_pk_fma_f32 v[58:59], v[198:199], v[50:51], v[58:59] op_sel_hi:[0,1,1]
	v_pk_fma_f32 v[72:73], v[198:199], v[52:53], v[72:73] op_sel_hi:[0,1,1]
	s_waitcnt lgkmcnt(7)
	v_pk_fma_f32 v[66:67], v[66:67], v[42:43], v[58:59]
	v_pk_fma_f32 v[64:65], v[64:65], v[44:45], v[72:73]
	v_pk_fma_f32 v[212:213], v[198:199], v[54:55], v[212:213] op_sel_hi:[0,1,1]
	v_pk_fma_f32 v[250:251], v[198:199], v[56:57], v[250:251] op_sel_hi:[0,1,1]
	v_pk_fma_f32 v[62:63], v[62:63], v[46:47], v[212:213]
	v_pk_fma_f32 v[60:61], v[60:61], v[48:49], v[250:251]
	ds_read_b128 v[50:53], v0 offset:24064
	ds_read_b128 v[54:57], v0 offset:24080
	ds_read_b128 v[42:45], v0 offset:7680
	ds_read_b128 v[46:49], v0 offset:7696
	s_waitcnt lgkmcnt(9)
; DI float oct_sum(float v) { v += dpp_f<0xB1>(v); v += dpp_f<0x4E>(v); v += dpp_f<0x141>(v); return v; }
; DI void scan_item(const Params& p, int b, int h, int half, char* smem, unsigned* pgen, unsigned kp) {
;     ...
;       for (int s4 = 0; s4 < 4; ++s4) {
;         const int s = sg + s4;
;         const f32x2* a2 = (const f32x2*)(Al + s * 64 + cg * 8);
;         const f32x2* w2 = (const f32x2*)(Wl + s * 64 + cg * 8);
;         const f32x2* b2 = (const f32x2*)(Bl + s * 64 + cg * 8);
;         const f32x2* k2 = (const f32x2*)(Kl + s * 64 + cg * 8);
;         const f32x2* r2 = (const f32x2*)(Rl + s * 64 + cg * 8);
;         f32x2 o[20];
; #pragma unroll
;         for (int i = 0; i < 4; ++i) { o[i] = a2[i]; o[4 + i] = w2[i]; o[8 + i] = b2[i]; o[12 + i] = k2[i]; o[16 + i] = r2[i]; }
;         const float vr = Vl[s * 64 + 32 * half + rp];
;         f32x2 p0 = St[0] * o[0], p1 = St[1] * o[1];
;         p0 = __builtin_elementwise_fma(St[2], o[2], p0); p1 = __builtin_elementwise_fma(St[3], o[3], p1);
;         const float sa = oct_sum((p0.x + p0.y) + (p1.x + p1.y));
;         const f32x2 sv = {sa, sa}, vv = {vr, vr};
;         f32x2 y0 = {0.f, 0.f}, y1 = {0.f, 0.f};
; #pragma unroll
;         for (int i = 0; i < 4; i += 2) {
;           St[i] = __builtin_elementwise_fma(St[i], o[4 + i], __builtin_elementwise_fma(sv, o[8 + i], vv * o[12 + i]));
;           St[i + 1] = __builtin_elementwise_fma(St[i + 1], o[5 + i], __builtin_elementwise_fma(sv, o[9 + i], vv * o[13 + i]));
;           y0 = __builtin_elementwise_fma(St[i], o[16 + i], y0);
;           y1 = __builtin_elementwise_fma(St[i + 1], o[17 + i], y1);
;         }
;         yy[s4] = oct_sum((y0.x + y0.y) + (y1.x + y1.y));
;       }
;       if (cg == 0) {
; #pragma unroll
;         for (int s4 = 0; s4 < 4; ++s4) Yl[(sg + s4) * 32 + rp] = yy[s4];
	v_pk_fma_f32 v[58:59], v[66:67], v[154:155], 0 op_sel_hi:[1,1,0]
	v_pk_fma_f32 v[72:73], v[64:65], v[156:157], 0 op_sel_hi:[1,1,0]
	v_pk_fma_f32 v[58:59], v[62:63], v[246:247], v[58:59]
	v_pk_fma_f32 v[72:73], v[60:61], v[248:249], v[72:73]
	ds_read_b128 v[154:157], v0 offset:3584
	ds_read_b128 v[246:249], v0 offset:3600
	v_pk_add_f32 v[58:59], v[58:59], v[72:73]
	ds_read_b128 v[200:203], v0 offset:20224
	ds_read_b128 v[230:233], v0 offset:20240
	s_waitcnt lgkmcnt(11)
	v_pk_mul_f32 v[34:35], v[66:67], v[34:35]
	v_pk_mul_f32 v[36:37], v[64:65], v[36:37]
	v_pk_fma_f32 v[34:35], v[62:63], v[38:39], v[34:35]
	v_pk_fma_f32 v[36:37], v[60:61], v[40:41], v[36:37]
	v_pk_add_f32 v[34:35], v[34:35], v[36:37]
	v_add_f32_e32 v207, v58, v59
	v_add_f32_e32 v198, v34, v35
	s_waitcnt lgkmcnt(8)
	v_pk_mul_f32 v[58:59], v[68:69], v[158:159] op_sel_hi:[1,0]
	v_pk_mul_f32 v[72:73], v[70:71], v[158:159] op_sel_hi:[1,0]
	ds_read_b128 v[68:71], v0 offset:12032
	v_add_f32_dpp v198, v198, v198 quad_perm:[1,0,3,2] row_mask:0xf bank_mask:0xf bound_ctrl:1
	v_add_f32_dpp v207, v207, v207 quad_perm:[1,0,3,2] row_mask:0xf bank_mask:0xf bound_ctrl:1
	v_pk_mul_f32 v[212:213], v[150:151], v[158:159] op_sel_hi:[1,0]
	v_add_f32_dpp v198, v198, v198 quad_perm:[2,3,0,1] row_mask:0xf bank_mask:0xf bound_ctrl:1
	v_add_f32_dpp v207, v207, v207 quad_perm:[2,3,0,1] row_mask:0xf bank_mask:0xf bound_ctrl:1
	v_pk_mul_f32 v[250:251], v[152:153], v[158:159] op_sel_hi:[1,0]
	ds_read_b128 v[150:153], v0 offset:12048
	v_add_f32_dpp v198, v198, v198 row_half_mirror row_mask:0xf bank_mask:0xf bound_ctrl:1
	v_add_f32_dpp v205, v207, v207 row_half_mirror row_mask:0xf bank_mask:0xf bound_ctrl:1
	ds_write_b32 v162, v205 offset:1664
	s_waitcnt lgkmcnt(8)
	v_pk_fma_f32 v[58:59], v[198:199], v[50:51], v[58:59] op_sel_hi:[0,1,1]
	v_pk_fma_f32 v[72:73], v[198:199], v[52:53], v[72:73] op_sel_hi:[0,1,1]
	s_waitcnt lgkmcnt(6)
	v_pk_fma_f32 v[66:67], v[66:67], v[42:43], v[58:59]
	v_pk_fma_f32 v[64:65], v[64:65], v[44:45], v[72:73]
	v_pk_fma_f32 v[212:213], v[198:199], v[54:55], v[212:213] op_sel_hi:[0,1,1]
	v_pk_fma_f32 v[250:251], v[198:199], v[56:57], v[250:251] op_sel_hi:[0,1,1]
	v_pk_fma_f32 v[62:63], v[62:63], v[46:47], v[212:213]
	v_pk_fma_f32 v[60:61], v[60:61], v[48:49], v[250:251]
	ds_read_b128 v[50:53], v0 offset:24320
	ds_read_b128 v[54:57], v0 offset:24336
	ds_read_b128 v[42:45], v0 offset:7936
	ds_read_b128 v[46:49], v0 offset:7952
	s_waitcnt lgkmcnt(8)
	v_pk_fma_f32 v[58:59], v[66:67], v[154:155], 0 op_sel_hi:[1,1,0]
	v_pk_fma_f32 v[72:73], v[64:65], v[156:157], 0 op_sel_hi:[1,1,0]
	v_pk_fma_f32 v[58:59], v[62:63], v[246:247], v[58:59]
	v_pk_fma_f32 v[72:73], v[60:61], v[248:249], v[72:73]
	ds_read_b128 v[154:157], v0 offset:3840
	ds_read_b128 v[246:249], v0 offset:3856
	v_pk_add_f32 v[58:59], v[58:59], v[72:73]
	s_waitcnt lgkmcnt(8)
	v_pk_mul_f32 v[200:201], v[66:67], v[200:201]
	v_pk_mul_f32 v[202:203], v[64:65], v[202:203]
	v_pk_fma_f32 v[200:201], v[62:63], v[230:231], v[200:201]
	v_pk_fma_f32 v[202:203], v[60:61], v[232:233], v[202:203]
	v_pk_add_f32 v[200:201], v[200:201], v[202:203]
	v_add_f32_e32 v207, v58, v59
	v_add_f32_e32 v198, v200, v201
	s_waitcnt lgkmcnt(6)
	v_mov_b32_e32 v232, v159
	v_pk_mul_f32 v[58:59], v[68:69], v[232:233] op_sel_hi:[1,0]
	v_pk_mul_f32 v[72:73], v[70:71], v[232:233] op_sel_hi:[1,0]
	v_add_f32_dpp v198, v198, v198 quad_perm:[1,0,3,2] row_mask:0xf bank_mask:0xf bound_ctrl:1
	v_add_f32_dpp v207, v207, v207 quad_perm:[1,0,3,2] row_mask:0xf bank_mask:0xf bound_ctrl:1
	v_pk_mul_f32 v[212:213], v[150:151], v[232:233] op_sel_hi:[1,0]
	v_add_f32_dpp v198, v198, v198 quad_perm:[2,3,0,1] row_mask:0xf bank_mask:0xf bound_ctrl:1
	v_add_f32_dpp v207, v207, v207 quad_perm:[2,3,0,1] row_mask:0xf bank_mask:0xf bound_ctrl:1
	v_pk_mul_f32 v[250:251], v[152:153], v[232:233] op_sel_hi:[1,0]
	v_add_f32_dpp v198, v198, v198 row_half_mirror row_mask:0xf bank_mask:0xf bound_ctrl:1
	v_add_f32_dpp v163, v207, v207 row_half_mirror row_mask:0xf bank_mask:0xf bound_ctrl:1
	ds_write_b32 v162, v163 offset:1792
	s_waitcnt lgkmcnt(4)
	v_pk_fma_f32 v[58:59], v[198:199], v[50:51], v[58:59] op_sel_hi:[0,1,1]
	v_pk_fma_f32 v[72:73], v[198:199], v[52:53], v[72:73] op_sel_hi:[0,1,1]
	s_waitcnt lgkmcnt(2)
	v_pk_fma_f32 v[66:67], v[66:67], v[42:43], v[58:59]
	v_pk_fma_f32 v[64:65], v[64:65], v[44:45], v[72:73]
	v_pk_fma_f32 v[212:213], v[198:199], v[54:55], v[212:213] op_sel_hi:[0,1,1]
	v_pk_fma_f32 v[250:251], v[198:199], v[56:57], v[250:251] op_sel_hi:[0,1,1]
	v_pk_fma_f32 v[62:63], v[62:63], v[46:47], v[212:213]
	v_pk_fma_f32 v[60:61], v[60:61], v[48:49], v[250:251]
	s_waitcnt lgkmcnt(0)
	v_pk_fma_f32 v[58:59], v[66:67], v[154:155], 0 op_sel_hi:[1,1,0]
	v_pk_fma_f32 v[72:73], v[64:65], v[156:157], 0 op_sel_hi:[1,1,0]
	v_pk_fma_f32 v[58:59], v[62:63], v[246:247], v[58:59]
	v_pk_fma_f32 v[72:73], v[60:61], v[248:249], v[72:73]
	v_pk_add_f32 v[58:59], v[58:59], v[72:73]
	s_nop 0
	v_add_f32_e32 v207, v58, v59
	s_nop 1
	v_add_f32_dpp v207, v207, v207 quad_perm:[1,0,3,2] row_mask:0xf bank_mask:0xf bound_ctrl:1
	s_nop 1
	v_add_f32_dpp v207, v207, v207 quad_perm:[2,3,0,1] row_mask:0xf bank_mask:0xf bound_ctrl:1
	s_nop 1
	v_add_f32_dpp v205, v207, v207 row_half_mirror row_mask:0xf bank_mask:0xf bound_ctrl:1
	ds_write_b32 v162, v205 offset:1920
